# moe1 / g1 gate fast-division epilogues: v_mov after the division folded into its single consumer (97 sites)
# speedup vs baseline: 1.0027x; 1.0002x over previous
; DI unsigned pack2(float a, float b) { fl2_t f = {a, b}; bf2_t r = __builtin_convertvector(f, bf2_t); return __builtin_bit_cast(unsigned, r); }
; DI float sigmoidf_(float x) { return 1.f / (1.f + __expf(-x)); }
; DI void g1_phase(const P& p, int l, unsigned char* lds) {
;     ...
;     if (tn_ >= 10) {
;       const int br = (tn_ - 10) >> 2, tn2 = ((tn_ - 10) & 3) * 2 + (wn >> 1), wn2 = wn & 1;
;       u16* gf = (u16*)(p.ws + O_GF) + (size_t)br * TA * 1024;
; #pragma unroll
;       for (int mt = 0; mt < 4; ++mt) {
;         const int wave2 = (2 * wm + (mt >> 1)) * 2 + wn2, mt2 = mt & 1;
; #pragma unroll
;         for (int nt = 0; nt < 2; ++nt)
; #pragma unroll
;           for (int g4 = 0; g4 < 4; ++g4) {
;             size_t idx = ((((((size_t)tm_ * 8 + tn2) * 8 + wave2) * 2 + mt2) * 2 + nt) * 4 + g4) * 64 + lane;
;             *(uint2*)(gf + idx * 4) = make_uint2(pack2(sigmoidf_(acc[mt][nt][4 * g4]), sigmoidf_(acc[mt][nt][4 * g4 + 1])),
;                                                  pack2(sigmoidf_(acc[mt][nt][4 * g4 + 2]), sigmoidf_(acc[mt][nt][4 * g4 + 3])));
;           }
;       }
.LBB0_228:
	s_andn2_b64 vcc, exec, s[0:1]
	s_cbranch_vccnz .LBB0_230
	s_nop 7
	s_nop 7
	v_min_f32_e32 v150, v2, v3
	v_min3_f32 v150, v150, v4, v5
	v_min3_f32 v150, v150, v6, v7
	v_min3_f32 v150, v150, v8, v9
	v_min3_f32 v150, v150, v10, v11
	v_min3_f32 v150, v150, v12, v13
	v_min3_f32 v150, v150, v14, v15
	v_min3_f32 v150, v150, v16, v17
	v_min3_f32 v150, v150, v18, v19
	v_min3_f32 v150, v150, v20, v21
	v_min3_f32 v150, v150, v22, v23
	v_min3_f32 v150, v150, v24, v25
	v_min3_f32 v150, v150, v26, v27
	v_min3_f32 v150, v150, v28, v29
	v_min3_f32 v150, v150, v30, v31
	v_min3_f32 v150, v150, v32, v33
	v_min3_f32 v150, v150, v34, v35
	v_min3_f32 v150, v150, v36, v37
	v_min3_f32 v150, v150, v38, v39
	v_min3_f32 v150, v150, v40, v41
	v_min3_f32 v150, v150, v42, v43
	v_min3_f32 v150, v150, v44, v45
	v_min3_f32 v150, v150, v46, v47
	v_min3_f32 v150, v150, v48, v49
	v_min3_f32 v150, v150, v50, v51
	v_min3_f32 v150, v150, v52, v53
	v_min3_f32 v150, v150, v54, v55
	v_min3_f32 v150, v150, v56, v57
	v_min3_f32 v150, v150, v58, v59
	v_min3_f32 v150, v150, v60, v61
	v_min3_f32 v150, v150, v62, v63
	v_min3_f32 v150, v150, v64, v65
	v_min3_f32 v150, v150, v66, v67
	v_min3_f32 v150, v150, v68, v69
	v_min3_f32 v150, v150, v70, v71
	v_min3_f32 v150, v150, v72, v73
	v_min3_f32 v150, v150, v74, v75
	v_min3_f32 v150, v150, v76, v77
	v_min3_f32 v150, v150, v78, v79
	v_min3_f32 v150, v150, v80, v81
	v_min3_f32 v150, v150, v82, v83
	v_min3_f32 v150, v150, v84, v85
	v_min3_f32 v150, v150, v86, v87
	v_min3_f32 v150, v150, v88, v89
	v_min3_f32 v150, v150, v90, v91
	v_min3_f32 v150, v150, v92, v93
	v_min3_f32 v150, v150, v94, v95
	v_min3_f32 v150, v150, v96, v97
	v_min3_f32 v150, v150, v98, v99
	v_min3_f32 v150, v150, v100, v101
	v_min3_f32 v150, v150, v102, v103
	v_min3_f32 v150, v150, v104, v105
	v_min3_f32 v150, v150, v106, v107
	v_min3_f32 v150, v150, v108, v109
	v_min3_f32 v150, v150, v110, v111
	v_min3_f32 v150, v150, v112, v113
	v_min3_f32 v150, v150, v114, v115
	v_min3_f32 v150, v150, v116, v117
	v_min3_f32 v150, v150, v118, v119
	v_min3_f32 v150, v150, v120, v121
	v_min3_f32 v150, v150, v122, v123
	v_min3_f32 v150, v150, v124, v125
	v_min3_f32 v150, v150, v126, v127
	v_min3_f32 v150, v150, v128, v129
	v_mov_b32_e32 v151, 0xc2700000
	s_nop 0
	v_cmp_nlt_f32_e32 vcc, v151, v150
	s_cbranch_vccnz .Lg1_gate_slow
	s_add_i32 s0, s10, -10
	s_lshr_b32 s1, s0, 2
	s_lshl_b32 s0, s0, 1
	v_lshrrev_b32_e32 v130, 1, v139
	s_mul_hi_u32 s5, s1, 0x4200000
	s_mul_i32 s1, s1, 0x4200000
	v_and_or_b32 v131, s0, 6, v130
	v_bfe_u32 v130, v137, 6, 1
	s_add_u32 s0, s95, s1
	s_addc_u32 s1, s33, s5
	v_lshl_or_b32 v130, v140, 2, v130
	s_lshl_b32 s5, s25, 6
	v_lshl_or_b32 v178, v131, 3, s5
	v_ashrrev_i32_e32 v131, 31, v130
	v_lshl_add_u64 v[132:133], v[178:179], 0, v[130:131]
	v_mul_f32_e32 v131, 0xbfb8aa3b, v2
	v_exp_f32_e32 v134, v131
	v_mul_f32_e32 v131, 0xbfb8aa3b, v3
	v_exp_f32_e32 v135, v131
	v_or_b32_e32 v130, 2, v130
	v_pk_add_f32 v[134:135], v[134:135], 1.0 op_sel_hi:[1,0]
	s_nop 0
	v_rcp_f32_e32 v141, v135
	s_waitcnt vmcnt(4)
	v_fma_f32 v142, -v135, v141, 1.0
	v_fmac_f32_e32 v141, v142, v141
	v_fma_f32 v144, -v135, v141, 1.0
	v_fma_f32 v143, v144, v141, v141
	v_fma_f32 v131, -v135, v143, 1.0
	v_fma_f32 v131, v131, v141, v143
	v_rcp_f32_e32 v141, v134
	s_nop 0
	v_fma_f32 v142, -v134, v141, 1.0
	v_fmac_f32_e32 v141, v142, v141
	v_fma_f32 v144, -v134, v141, 1.0
	v_fma_f32 v143, v144, v141, v141
	v_fma_f32 v135, -v134, v143, 1.0
	v_fma_f32 v135, v135, v141, v143
	v_cvt_pk_bf16_f32 v142, v135, v131
	v_mul_f32_e32 v131, 0xbfb8aa3b, v4
	v_exp_f32_e32 v134, v131
	v_mul_f32_e32 v131, 0xbfb8aa3b, v5
	v_exp_f32_e32 v135, v131
	s_nop 0
	v_pk_add_f32 v[134:135], v[134:135], 1.0 op_sel_hi:[1,0]
	s_nop 0
	v_rcp_f32_e32 v141, v135
	s_nop 0
	v_fma_f32 v143, -v135, v141, 1.0
	v_fmac_f32_e32 v141, v143, v141
	v_fma_f32 v145, -v135, v141, 1.0
	v_fma_f32 v144, v145, v141, v141
	v_fma_f32 v131, -v135, v144, 1.0
	v_fma_f32 v131, v131, v141, v144
	v_rcp_f32_e32 v141, v134
	s_nop 0
	v_fma_f32 v143, -v134, v141, 1.0
	v_fmac_f32_e32 v141, v143, v141
	v_fma_f32 v145, -v134, v141, 1.0
	v_fma_f32 v144, v145, v141, v141
	v_fma_f32 v135, -v134, v144, 1.0
	v_fma_f32 v135, v135, v141, v144
	v_cvt_pk_bf16_f32 v143, v135, v131
	v_lshlrev_b64 v[134:135], 13, v[132:133]
	v_lshlrev_b32_e32 v132, 3, v1
	v_mov_b32_e32 v133, v179
	v_lshl_add_u64 v[134:135], s[0:1], 0, v[134:135]
	v_lshl_add_u64 v[134:135], v[134:135], 0, v[132:133]
	v_mul_f32_e32 v131, 0xbfb8aa3b, v6
	global_store_dwordx2 v[134:135], v[142:143], off
	v_exp_f32_e32 v142, v131
	v_mul_f32_e32 v131, 0xbfb8aa3b, v7
	v_exp_f32_e32 v143, v131
	s_nop 0
	v_pk_add_f32 v[142:143], v[142:143], 1.0 op_sel_hi:[1,0]
	s_nop 0
	v_rcp_f32_e32 v141, v143
	s_nop 0
	v_fma_f32 v144, -v143, v141, 1.0
	v_fmac_f32_e32 v141, v144, v141
	s_waitcnt vmcnt(4)
; DI unsigned pack2(float a, float b) { fl2_t f = {a, b}; bf2_t r = __builtin_convertvector(f, bf2_t); return __builtin_bit_cast(unsigned, r); }
; DI float sigmoidf_(float x) { return 1.f / (1.f + __expf(-x)); }
; DI void g1_phase(const P& p, int l, unsigned char* lds) {
;     ...
; #pragma unroll
;       for (int mt = 0; mt < 4; ++mt) {
;         const int wave2 = (2 * wm + (mt >> 1)) * 2 + wn2, mt2 = mt & 1;
; #pragma unroll
;         for (int nt = 0; nt < 2; ++nt)
; #pragma unroll
;           for (int g4 = 0; g4 < 4; ++g4) {
;             size_t idx = ((((((size_t)tm_ * 8 + tn2) * 8 + wave2) * 2 + mt2) * 2 + nt) * 4 + g4) * 64 + lane;
;             *(uint2*)(gf + idx * 4) = make_uint2(pack2(sigmoidf_(acc[mt][nt][4 * g4]), sigmoidf_(acc[mt][nt][4 * g4 + 1])),
;                                                  pack2(sigmoidf_(acc[mt][nt][4 * g4 + 2]), sigmoidf_(acc[mt][nt][4 * g4 + 3])));
;           }
	v_fma_f32 v146, -v143, v141, 1.0
	v_fma_f32 v145, v146, v141, v141
	v_fma_f32 v131, -v143, v145, 1.0
	v_fma_f32 v131, v131, v141, v145
	v_rcp_f32_e32 v143, v142
	s_nop 0
	v_fma_f32 v144, -v142, v143, 1.0
	v_fmac_f32_e32 v143, v144, v143
	v_fma_f32 v146, -v142, v143, 1.0
	v_fma_f32 v145, v146, v143, v143
	v_fma_f32 v141, -v142, v145, 1.0
	v_fma_f32 v141, v141, v143, v145
	v_cvt_pk_bf16_f32 v142, v141, v131
	v_mul_f32_e32 v131, 0xbfb8aa3b, v8
	v_exp_f32_e32 v144, v131
	v_mul_f32_e32 v131, 0xbfb8aa3b, v9
	v_exp_f32_e32 v145, v131
	s_nop 0
	v_pk_add_f32 v[144:145], v[144:145], 1.0 op_sel_hi:[1,0]
	s_nop 0
	v_rcp_f32_e32 v141, v145
	s_nop 0
	v_fma_f32 v143, -v145, v141, 1.0
	v_fmac_f32_e32 v141, v143, v141
	v_fma_f32 v147, -v145, v141, 1.0
	v_fma_f32 v146, v147, v141, v141
	v_fma_f32 v131, -v145, v146, 1.0
	v_fma_f32 v131, v131, v141, v146
	v_rcp_f32_e32 v143, v144
	s_nop 0
	v_fma_f32 v145, -v144, v143, 1.0
	v_fmac_f32_e32 v143, v145, v143
	v_fma_f32 v147, -v144, v143, 1.0
	v_fma_f32 v146, v147, v143, v143
	v_fma_f32 v141, -v144, v146, 1.0
	v_fma_f32 v141, v141, v143, v146
	v_cvt_pk_bf16_f32 v143, v141, v131
	v_mul_f32_e32 v131, 0xbfb8aa3b, v10
	global_store_dwordx2 v[134:135], v[142:143], off offset:512
	v_exp_f32_e32 v142, v131
	v_mul_f32_e32 v131, 0xbfb8aa3b, v11
	v_exp_f32_e32 v143, v131
	s_nop 0
	v_pk_add_f32 v[142:143], v[142:143], 1.0 op_sel_hi:[1,0]
	s_nop 0
	v_rcp_f32_e32 v141, v143
	s_nop 0
	v_fma_f32 v144, -v143, v141, 1.0
	v_fmac_f32_e32 v141, v144, v141
	v_fma_f32 v146, -v143, v141, 1.0
	v_fma_f32 v145, v146, v141, v141
	v_fma_f32 v131, -v143, v145, 1.0
	v_fma_f32 v131, v131, v141, v145
	v_rcp_f32_e32 v143, v142
	s_nop 0
	v_fma_f32 v144, -v142, v143, 1.0
	v_fmac_f32_e32 v143, v144, v143
	v_fma_f32 v146, -v142, v143, 1.0
	v_fma_f32 v145, v146, v143, v143
	v_fma_f32 v141, -v142, v145, 1.0
	v_fma_f32 v141, v141, v143, v145
	v_cvt_pk_bf16_f32 v142, v141, v131
	v_mul_f32_e32 v131, 0xbfb8aa3b, v12
	v_exp_f32_e32 v144, v131
	v_mul_f32_e32 v131, 0xbfb8aa3b, v13
	v_exp_f32_e32 v145, v131
	s_nop 0
	v_pk_add_f32 v[144:145], v[144:145], 1.0 op_sel_hi:[1,0]
	s_nop 0
	v_rcp_f32_e32 v141, v145
	s_nop 0
	v_fma_f32 v143, -v145, v141, 1.0
	v_fmac_f32_e32 v141, v143, v141
	v_fma_f32 v147, -v145, v141, 1.0
	v_fma_f32 v146, v147, v141, v141
	v_fma_f32 v131, -v145, v146, 1.0
	v_fma_f32 v131, v131, v141, v146
	v_rcp_f32_e32 v143, v144
	s_nop 0
	v_fma_f32 v145, -v144, v143, 1.0
	v_fmac_f32_e32 v143, v145, v143
	v_fma_f32 v147, -v144, v143, 1.0
	v_fma_f32 v146, v147, v143, v143
	v_fma_f32 v141, -v144, v146, 1.0
	v_fma_f32 v141, v141, v143, v146
	v_cvt_pk_bf16_f32 v143, v141, v131
	v_mul_f32_e32 v131, 0xbfb8aa3b, v14
	global_store_dwordx2 v[134:135], v[142:143], off offset:1024
	v_exp_f32_e32 v142, v131
	v_mul_f32_e32 v131, 0xbfb8aa3b, v15
	v_exp_f32_e32 v143, v131
	s_nop 0
	v_pk_add_f32 v[142:143], v[142:143], 1.0 op_sel_hi:[1,0]
	s_nop 0
	v_rcp_f32_e32 v141, v143
	s_nop 0
	v_fma_f32 v144, -v143, v141, 1.0
	v_fmac_f32_e32 v141, v144, v141
	v_fma_f32 v146, -v143, v141, 1.0
	v_fma_f32 v145, v146, v141, v141
	v_fma_f32 v131, -v143, v145, 1.0
	v_fma_f32 v131, v131, v141, v145
	v_rcp_f32_e32 v143, v142
	s_nop 0
	v_fma_f32 v144, -v142, v143, 1.0
	v_fmac_f32_e32 v143, v144, v143
	v_fma_f32 v146, -v142, v143, 1.0
	v_fma_f32 v145, v146, v143, v143
	v_fma_f32 v141, -v142, v145, 1.0
	v_fma_f32 v141, v141, v143, v145
	v_cvt_pk_bf16_f32 v142, v141, v131
	v_mul_f32_e32 v131, 0xbfb8aa3b, v16
	v_exp_f32_e32 v144, v131
	v_mul_f32_e32 v131, 0xbfb8aa3b, v17
	v_exp_f32_e32 v145, v131
	s_nop 0
	v_pk_add_f32 v[144:145], v[144:145], 1.0 op_sel_hi:[1,0]
	s_nop 0
	v_rcp_f32_e32 v141, v145
	s_nop 0
	v_fma_f32 v143, -v145, v141, 1.0
	v_fmac_f32_e32 v141, v143, v141
	v_fma_f32 v147, -v145, v141, 1.0
	v_fma_f32 v146, v147, v141, v141
	v_fma_f32 v131, -v145, v146, 1.0
	v_fma_f32 v131, v131, v141, v146
	v_rcp_f32_e32 v143, v144
	s_nop 0
	v_fma_f32 v145, -v144, v143, 1.0
	v_fmac_f32_e32 v143, v145, v143
	v_fma_f32 v147, -v144, v143, 1.0
	v_fma_f32 v146, v147, v143, v143
	v_fma_f32 v141, -v144, v146, 1.0
	v_fma_f32 v141, v141, v143, v146
	v_cvt_pk_bf16_f32 v143, v141, v131
	v_mul_f32_e32 v131, 0xbfb8aa3b, v18
	global_store_dwordx2 v[134:135], v[142:143], off offset:1536
	v_exp_f32_e32 v142, v131
	v_mul_f32_e32 v131, 0xbfb8aa3b, v19
	v_exp_f32_e32 v143, v131
	s_nop 0
	v_pk_add_f32 v[142:143], v[142:143], 1.0 op_sel_hi:[1,0]
	s_nop 0
	v_rcp_f32_e32 v141, v143
	s_nop 0
	v_fma_f32 v144, -v143, v141, 1.0
	v_fmac_f32_e32 v141, v144, v141
	v_fma_f32 v146, -v143, v141, 1.0
	v_fma_f32 v145, v146, v141, v141
	v_fma_f32 v131, -v143, v145, 1.0
	v_fma_f32 v131, v131, v141, v145
	v_rcp_f32_e32 v143, v142
	s_nop 0
	v_fma_f32 v144, -v142, v143, 1.0
	v_fmac_f32_e32 v143, v144, v143
	v_fma_f32 v146, -v142, v143, 1.0
	v_fma_f32 v145, v146, v143, v143
	v_fma_f32 v141, -v142, v145, 1.0
	v_fma_f32 v141, v141, v143, v145
	v_cvt_pk_bf16_f32 v142, v141, v131
	v_mul_f32_e32 v131, 0xbfb8aa3b, v20
	v_exp_f32_e32 v144, v131
	v_mul_f32_e32 v131, 0xbfb8aa3b, v21
	v_exp_f32_e32 v145, v131
	s_nop 0
	v_pk_add_f32 v[144:145], v[144:145], 1.0 op_sel_hi:[1,0]
	s_nop 0
	v_rcp_f32_e32 v141, v145
	s_nop 0
	v_fma_f32 v143, -v145, v141, 1.0
	v_fmac_f32_e32 v141, v143, v141
	v_fma_f32 v147, -v145, v141, 1.0
	v_fma_f32 v146, v147, v141, v141
	v_fma_f32 v131, -v145, v146, 1.0
	v_fma_f32 v131, v131, v141, v146
	v_rcp_f32_e32 v143, v144
	s_nop 0
	v_fma_f32 v145, -v144, v143, 1.0
	v_fmac_f32_e32 v143, v145, v143
	v_fma_f32 v147, -v144, v143, 1.0
	v_fma_f32 v146, v147, v143, v143
	v_fma_f32 v141, -v144, v146, 1.0
	v_fma_f32 v141, v141, v143, v146
	v_cvt_pk_bf16_f32 v143, v141, v131
	v_mul_f32_e32 v131, 0xbfb8aa3b, v22
; DI unsigned pack2(float a, float b) { fl2_t f = {a, b}; bf2_t r = __builtin_convertvector(f, bf2_t); return __builtin_bit_cast(unsigned, r); }
; DI float sigmoidf_(float x) { return 1.f / (1.f + __expf(-x)); }
; DI void g1_phase(const P& p, int l, unsigned char* lds) {
;     ...
; #pragma unroll
;       for (int mt = 0; mt < 4; ++mt) {
;         const int wave2 = (2 * wm + (mt >> 1)) * 2 + wn2, mt2 = mt & 1;
; #pragma unroll
;         for (int nt = 0; nt < 2; ++nt)
; #pragma unroll
;           for (int g4 = 0; g4 < 4; ++g4) {
;             size_t idx = ((((((size_t)tm_ * 8 + tn2) * 8 + wave2) * 2 + mt2) * 2 + nt) * 4 + g4) * 64 + lane;
;             *(uint2*)(gf + idx * 4) = make_uint2(pack2(sigmoidf_(acc[mt][nt][4 * g4]), sigmoidf_(acc[mt][nt][4 * g4 + 1])),
;                                                  pack2(sigmoidf_(acc[mt][nt][4 * g4 + 2]), sigmoidf_(acc[mt][nt][4 * g4 + 3])));
;           }
	global_store_dwordx2 v[134:135], v[142:143], off offset:2048
	v_exp_f32_e32 v142, v131
	v_mul_f32_e32 v131, 0xbfb8aa3b, v23
	v_exp_f32_e32 v143, v131
	s_nop 0
	v_pk_add_f32 v[142:143], v[142:143], 1.0 op_sel_hi:[1,0]
	s_nop 0
	v_rcp_f32_e32 v141, v143
	s_nop 0
	v_fma_f32 v144, -v143, v141, 1.0
	v_fmac_f32_e32 v141, v144, v141
	v_fma_f32 v146, -v143, v141, 1.0
	v_fma_f32 v145, v146, v141, v141
	v_fma_f32 v131, -v143, v145, 1.0
	v_fma_f32 v131, v131, v141, v145
	v_rcp_f32_e32 v143, v142
	s_nop 0
	v_fma_f32 v144, -v142, v143, 1.0
	v_fmac_f32_e32 v143, v144, v143
	v_fma_f32 v146, -v142, v143, 1.0
	v_fma_f32 v145, v146, v143, v143
	v_fma_f32 v141, -v142, v145, 1.0
	v_fma_f32 v141, v141, v143, v145
	v_cvt_pk_bf16_f32 v142, v141, v131
	v_mul_f32_e32 v131, 0xbfb8aa3b, v24
	v_exp_f32_e32 v144, v131
	v_mul_f32_e32 v131, 0xbfb8aa3b, v25
	v_exp_f32_e32 v145, v131
	s_nop 0
	v_pk_add_f32 v[144:145], v[144:145], 1.0 op_sel_hi:[1,0]
	s_nop 0
	v_rcp_f32_e32 v141, v145
	s_nop 0
	v_fma_f32 v143, -v145, v141, 1.0
	v_fmac_f32_e32 v141, v143, v141
	v_fma_f32 v147, -v145, v141, 1.0
	v_fma_f32 v146, v147, v141, v141
	v_fma_f32 v131, -v145, v146, 1.0
	v_fma_f32 v131, v131, v141, v146
	v_rcp_f32_e32 v143, v144
	s_nop 0
	v_fma_f32 v145, -v144, v143, 1.0
	v_fmac_f32_e32 v143, v145, v143
	v_fma_f32 v147, -v144, v143, 1.0
	v_fma_f32 v146, v147, v143, v143
	v_fma_f32 v141, -v144, v146, 1.0
	v_fma_f32 v141, v141, v143, v146
	v_cvt_pk_bf16_f32 v143, v141, v131
	v_mul_f32_e32 v131, 0xbfb8aa3b, v26
	global_store_dwordx2 v[134:135], v[142:143], off offset:2560
	v_exp_f32_e32 v142, v131
	v_mul_f32_e32 v131, 0xbfb8aa3b, v27
	v_exp_f32_e32 v143, v131
	s_nop 0
	v_pk_add_f32 v[142:143], v[142:143], 1.0 op_sel_hi:[1,0]
	s_nop 0
	v_rcp_f32_e32 v141, v143
	s_nop 0
	v_fma_f32 v144, -v143, v141, 1.0
	v_fmac_f32_e32 v141, v144, v141
	v_fma_f32 v146, -v143, v141, 1.0
	v_fma_f32 v145, v146, v141, v141
	v_fma_f32 v131, -v143, v145, 1.0
	v_fma_f32 v131, v131, v141, v145
	v_rcp_f32_e32 v143, v142
	s_nop 0
	v_fma_f32 v144, -v142, v143, 1.0
	v_fmac_f32_e32 v143, v144, v143
	v_fma_f32 v146, -v142, v143, 1.0
	v_fma_f32 v145, v146, v143, v143
	v_fma_f32 v141, -v142, v145, 1.0
	v_fma_f32 v141, v141, v143, v145
	v_cvt_pk_bf16_f32 v142, v141, v131
	v_mul_f32_e32 v131, 0xbfb8aa3b, v28
	v_exp_f32_e32 v144, v131
	v_mul_f32_e32 v131, 0xbfb8aa3b, v29
	v_exp_f32_e32 v145, v131
	s_nop 0
	v_pk_add_f32 v[144:145], v[144:145], 1.0 op_sel_hi:[1,0]
	s_nop 0
	v_rcp_f32_e32 v141, v145
	s_nop 0
	v_fma_f32 v143, -v145, v141, 1.0
	v_fmac_f32_e32 v141, v143, v141
	v_fma_f32 v147, -v145, v141, 1.0
	v_fma_f32 v146, v147, v141, v141
	v_fma_f32 v131, -v145, v146, 1.0
	v_fma_f32 v131, v131, v141, v146
	v_rcp_f32_e32 v143, v144
	s_nop 0
	v_fma_f32 v145, -v144, v143, 1.0
	v_fmac_f32_e32 v143, v145, v143
	v_fma_f32 v147, -v144, v143, 1.0
	v_fma_f32 v146, v147, v143, v143
	v_fma_f32 v141, -v144, v146, 1.0
	v_fma_f32 v141, v141, v143, v146
	v_cvt_pk_bf16_f32 v143, v141, v131
	v_mul_f32_e32 v131, 0xbfb8aa3b, v30
	global_store_dwordx2 v[134:135], v[142:143], off offset:3072
	v_exp_f32_e32 v142, v131
	v_mul_f32_e32 v131, 0xbfb8aa3b, v31
	v_exp_f32_e32 v143, v131
	s_nop 0
	v_pk_add_f32 v[142:143], v[142:143], 1.0 op_sel_hi:[1,0]
	s_nop 0
	v_rcp_f32_e32 v141, v143
	s_nop 0
	v_fma_f32 v144, -v143, v141, 1.0
	v_fmac_f32_e32 v141, v144, v141
	v_fma_f32 v146, -v143, v141, 1.0
	v_fma_f32 v145, v146, v141, v141
	v_fma_f32 v131, -v143, v145, 1.0
	v_fma_f32 v131, v131, v141, v145
	v_rcp_f32_e32 v143, v142
	s_nop 0
	v_fma_f32 v144, -v142, v143, 1.0
	v_fmac_f32_e32 v143, v144, v143
	v_fma_f32 v146, -v142, v143, 1.0
	v_fma_f32 v145, v146, v143, v143
	v_fma_f32 v141, -v142, v145, 1.0
	v_fma_f32 v141, v141, v143, v145
	v_cvt_pk_bf16_f32 v142, v141, v131
	v_mul_f32_e32 v131, 0xbfb8aa3b, v32
	v_exp_f32_e32 v144, v131
	v_mul_f32_e32 v131, 0xbfb8aa3b, v33
	v_exp_f32_e32 v145, v131
	s_nop 0
	v_pk_add_f32 v[144:145], v[144:145], 1.0 op_sel_hi:[1,0]
	s_nop 0
	v_rcp_f32_e32 v141, v145
	s_nop 0
	v_fma_f32 v143, -v145, v141, 1.0
	v_fmac_f32_e32 v141, v143, v141
	v_fma_f32 v147, -v145, v141, 1.0
	v_fma_f32 v146, v147, v141, v141
	v_fma_f32 v131, -v145, v146, 1.0
	v_fma_f32 v131, v131, v141, v146
	v_rcp_f32_e32 v143, v144
	s_nop 0
	v_fma_f32 v145, -v144, v143, 1.0
	v_fmac_f32_e32 v143, v145, v143
	v_fma_f32 v147, -v144, v143, 1.0
	v_fma_f32 v146, v147, v143, v143
	v_fma_f32 v141, -v144, v146, 1.0
	v_fma_f32 v141, v141, v143, v146
	v_cvt_pk_bf16_f32 v143, v141, v131
	v_mul_f32_e32 v131, 0xbfb8aa3b, v34
	global_store_dwordx2 v[134:135], v[142:143], off offset:3584
	v_exp_f32_e32 v142, v131
	v_mul_f32_e32 v131, 0xbfb8aa3b, v35
	v_exp_f32_e32 v143, v131
	s_nop 0
	v_pk_add_f32 v[142:143], v[142:143], 1.0 op_sel_hi:[1,0]
	s_nop 0
	v_rcp_f32_e32 v141, v143
	s_nop 0
	v_fma_f32 v144, -v143, v141, 1.0
	v_fmac_f32_e32 v141, v144, v141
	v_fma_f32 v146, -v143, v141, 1.0
	v_fma_f32 v145, v146, v141, v141
	v_fma_f32 v131, -v143, v145, 1.0
	v_fma_f32 v131, v131, v141, v145
	v_rcp_f32_e32 v143, v142
	s_nop 0
	v_fma_f32 v144, -v142, v143, 1.0
	v_fmac_f32_e32 v143, v144, v143
	v_fma_f32 v146, -v142, v143, 1.0
	v_fma_f32 v145, v146, v143, v143
	v_fma_f32 v141, -v142, v145, 1.0
	v_fma_f32 v141, v141, v143, v145
	v_cvt_pk_bf16_f32 v142, v141, v131
	v_mul_f32_e32 v131, 0xbfb8aa3b, v36
	v_exp_f32_e32 v144, v131
	v_mul_f32_e32 v131, 0xbfb8aa3b, v37
	v_exp_f32_e32 v145, v131
	s_nop 0
	v_pk_add_f32 v[144:145], v[144:145], 1.0 op_sel_hi:[1,0]
	s_nop 0
	v_rcp_f32_e32 v141, v145
	s_nop 0
	v_fma_f32 v143, -v145, v141, 1.0
	v_fmac_f32_e32 v141, v143, v141
	v_fma_f32 v147, -v145, v141, 1.0
	v_fma_f32 v146, v147, v141, v141
	v_fma_f32 v131, -v145, v146, 1.0
	v_fma_f32 v131, v131, v141, v146
; DI unsigned pack2(float a, float b) { fl2_t f = {a, b}; bf2_t r = __builtin_convertvector(f, bf2_t); return __builtin_bit_cast(unsigned, r); }
; DI float sigmoidf_(float x) { return 1.f / (1.f + __expf(-x)); }
; DI void g1_phase(const P& p, int l, unsigned char* lds) {
;     ...
; #pragma unroll
;       for (int mt = 0; mt < 4; ++mt) {
;         const int wave2 = (2 * wm + (mt >> 1)) * 2 + wn2, mt2 = mt & 1;
; #pragma unroll
;         for (int nt = 0; nt < 2; ++nt)
; #pragma unroll
;           for (int g4 = 0; g4 < 4; ++g4) {
;             size_t idx = ((((((size_t)tm_ * 8 + tn2) * 8 + wave2) * 2 + mt2) * 2 + nt) * 4 + g4) * 64 + lane;
;             *(uint2*)(gf + idx * 4) = make_uint2(pack2(sigmoidf_(acc[mt][nt][4 * g4]), sigmoidf_(acc[mt][nt][4 * g4 + 1])),
;                                                  pack2(sigmoidf_(acc[mt][nt][4 * g4 + 2]), sigmoidf_(acc[mt][nt][4 * g4 + 3])));
;           }
	v_rcp_f32_e32 v143, v144
	s_nop 0
	v_fma_f32 v145, -v144, v143, 1.0
	v_fmac_f32_e32 v143, v145, v143
	v_fma_f32 v147, -v144, v143, 1.0
	v_fma_f32 v146, v147, v143, v143
	v_fma_f32 v141, -v144, v146, 1.0
	v_fma_f32 v141, v141, v143, v146
	v_add_co_u32_e32 v134, vcc, s46, v134
	v_cvt_pk_bf16_f32 v143, v141, v131
	s_nop 0
	v_addc_co_u32_e32 v135, vcc, 0, v135, vcc
	v_mul_f32_e32 v131, 0xbfb8aa3b, v38
	global_store_dwordx2 v[134:135], v[142:143], off
	v_exp_f32_e32 v142, v131
	v_mul_f32_e32 v131, 0xbfb8aa3b, v39
	v_exp_f32_e32 v143, v131
	s_nop 0
	v_pk_add_f32 v[142:143], v[142:143], 1.0 op_sel_hi:[1,0]
	s_nop 0
	v_rcp_f32_e32 v141, v143
	s_nop 0
	v_fma_f32 v144, -v143, v141, 1.0
	v_fmac_f32_e32 v141, v144, v141
	v_fma_f32 v146, -v143, v141, 1.0
	v_fma_f32 v145, v146, v141, v141
	v_fma_f32 v131, -v143, v145, 1.0
	v_fma_f32 v131, v131, v141, v145
	v_rcp_f32_e32 v143, v142
	s_nop 0
	v_fma_f32 v144, -v142, v143, 1.0
	v_fmac_f32_e32 v143, v144, v143
	v_fma_f32 v146, -v142, v143, 1.0
	v_fma_f32 v145, v146, v143, v143
	v_fma_f32 v141, -v142, v145, 1.0
	v_fma_f32 v141, v141, v143, v145
	v_cvt_pk_bf16_f32 v142, v141, v131
	v_mul_f32_e32 v131, 0xbfb8aa3b, v40
	v_exp_f32_e32 v144, v131
	v_mul_f32_e32 v131, 0xbfb8aa3b, v41
	v_exp_f32_e32 v145, v131
	s_nop 0
	v_pk_add_f32 v[144:145], v[144:145], 1.0 op_sel_hi:[1,0]
	s_nop 0
	v_rcp_f32_e32 v141, v145
	s_nop 0
	v_fma_f32 v143, -v145, v141, 1.0
	v_fmac_f32_e32 v141, v143, v141
	v_fma_f32 v147, -v145, v141, 1.0
	v_fma_f32 v146, v147, v141, v141
	v_fma_f32 v131, -v145, v146, 1.0
	v_fma_f32 v131, v131, v141, v146
	v_rcp_f32_e32 v143, v144
	s_nop 0
	v_fma_f32 v145, -v144, v143, 1.0
	v_fmac_f32_e32 v143, v145, v143
	v_fma_f32 v147, -v144, v143, 1.0
	v_fma_f32 v146, v147, v143, v143
	v_fma_f32 v141, -v144, v146, 1.0
	v_fma_f32 v141, v141, v143, v146
	v_cvt_pk_bf16_f32 v143, v141, v131
	v_mul_f32_e32 v131, 0xbfb8aa3b, v42
	global_store_dwordx2 v[134:135], v[142:143], off offset:512
	v_exp_f32_e32 v142, v131
	v_mul_f32_e32 v131, 0xbfb8aa3b, v43
	v_exp_f32_e32 v143, v131
	s_nop 0
	v_pk_add_f32 v[142:143], v[142:143], 1.0 op_sel_hi:[1,0]
	s_nop 0
	v_rcp_f32_e32 v141, v143
	s_nop 0
	v_fma_f32 v144, -v143, v141, 1.0
	v_fmac_f32_e32 v141, v144, v141
	v_fma_f32 v146, -v143, v141, 1.0
	v_fma_f32 v145, v146, v141, v141
	v_fma_f32 v131, -v143, v145, 1.0
	v_fma_f32 v131, v131, v141, v145
	v_rcp_f32_e32 v143, v142
	s_nop 0
	v_fma_f32 v144, -v142, v143, 1.0
	v_fmac_f32_e32 v143, v144, v143
	v_fma_f32 v146, -v142, v143, 1.0
	v_fma_f32 v145, v146, v143, v143
	v_fma_f32 v141, -v142, v145, 1.0
	v_fma_f32 v141, v141, v143, v145
	v_cvt_pk_bf16_f32 v142, v141, v131
	v_mul_f32_e32 v131, 0xbfb8aa3b, v44
	v_exp_f32_e32 v144, v131
	v_mul_f32_e32 v131, 0xbfb8aa3b, v45
	v_exp_f32_e32 v145, v131
	s_nop 0
	v_pk_add_f32 v[144:145], v[144:145], 1.0 op_sel_hi:[1,0]
	s_nop 0
	v_rcp_f32_e32 v141, v145
	s_nop 0
	v_fma_f32 v143, -v145, v141, 1.0
	v_fmac_f32_e32 v141, v143, v141
	v_fma_f32 v147, -v145, v141, 1.0
	v_fma_f32 v146, v147, v141, v141
	v_fma_f32 v131, -v145, v146, 1.0
	v_fma_f32 v131, v131, v141, v146
	v_rcp_f32_e32 v143, v144
	s_nop 0
	v_fma_f32 v145, -v144, v143, 1.0
	v_fmac_f32_e32 v143, v145, v143
	v_fma_f32 v147, -v144, v143, 1.0
	v_fma_f32 v146, v147, v143, v143
	v_fma_f32 v141, -v144, v146, 1.0
	v_fma_f32 v141, v141, v143, v146
	v_cvt_pk_bf16_f32 v143, v141, v131
	v_mul_f32_e32 v131, 0xbfb8aa3b, v46
	global_store_dwordx2 v[134:135], v[142:143], off offset:1024
	v_exp_f32_e32 v142, v131
	v_mul_f32_e32 v131, 0xbfb8aa3b, v47
	v_exp_f32_e32 v143, v131
	s_nop 0
	v_pk_add_f32 v[142:143], v[142:143], 1.0 op_sel_hi:[1,0]
	s_nop 0
	v_rcp_f32_e32 v141, v143
	s_nop 0
	v_fma_f32 v144, -v143, v141, 1.0
	v_fmac_f32_e32 v141, v144, v141
	v_fma_f32 v146, -v143, v141, 1.0
	v_fma_f32 v145, v146, v141, v141
	v_fma_f32 v131, -v143, v145, 1.0
	v_fma_f32 v131, v131, v141, v145
	v_rcp_f32_e32 v143, v142
	s_nop 0
	v_fma_f32 v144, -v142, v143, 1.0
	v_fmac_f32_e32 v143, v144, v143
	v_fma_f32 v146, -v142, v143, 1.0
	v_fma_f32 v145, v146, v143, v143
	v_fma_f32 v141, -v142, v145, 1.0
	v_fma_f32 v141, v141, v143, v145
	v_cvt_pk_bf16_f32 v142, v141, v131
	v_mul_f32_e32 v131, 0xbfb8aa3b, v48
	v_exp_f32_e32 v144, v131
	v_mul_f32_e32 v131, 0xbfb8aa3b, v49
	v_exp_f32_e32 v145, v131
	s_nop 0
	v_pk_add_f32 v[144:145], v[144:145], 1.0 op_sel_hi:[1,0]
	s_nop 0
	v_rcp_f32_e32 v141, v145
	s_nop 0
	v_fma_f32 v143, -v145, v141, 1.0
	v_fmac_f32_e32 v141, v143, v141
	v_fma_f32 v147, -v145, v141, 1.0
	v_fma_f32 v146, v147, v141, v141
	v_fma_f32 v131, -v145, v146, 1.0
	v_fma_f32 v131, v131, v141, v146
	v_rcp_f32_e32 v143, v144
	s_nop 0
	v_fma_f32 v145, -v144, v143, 1.0
	v_fmac_f32_e32 v143, v145, v143
	v_fma_f32 v147, -v144, v143, 1.0
	v_fma_f32 v146, v147, v143, v143
	v_fma_f32 v141, -v144, v146, 1.0
	v_fma_f32 v141, v141, v143, v146
	v_cvt_pk_bf16_f32 v143, v141, v131
	v_mul_f32_e32 v131, 0xbfb8aa3b, v50
	global_store_dwordx2 v[134:135], v[142:143], off offset:1536
	v_exp_f32_e32 v142, v131
	v_mul_f32_e32 v131, 0xbfb8aa3b, v51
	v_exp_f32_e32 v143, v131
	s_nop 0
	v_pk_add_f32 v[142:143], v[142:143], 1.0 op_sel_hi:[1,0]
	s_nop 0
	v_rcp_f32_e32 v141, v143
	s_nop 0
	v_fma_f32 v144, -v143, v141, 1.0
	v_fmac_f32_e32 v141, v144, v141
	v_fma_f32 v146, -v143, v141, 1.0
	v_fma_f32 v145, v146, v141, v141
	v_fma_f32 v131, -v143, v145, 1.0
	v_fma_f32 v131, v131, v141, v145
	v_rcp_f32_e32 v143, v142
	s_nop 0
	v_fma_f32 v144, -v142, v143, 1.0
	v_fmac_f32_e32 v143, v144, v143
	v_fma_f32 v146, -v142, v143, 1.0
	v_fma_f32 v145, v146, v143, v143
	v_fma_f32 v141, -v142, v145, 1.0
	v_fma_f32 v141, v141, v143, v145
	v_cvt_pk_bf16_f32 v142, v141, v131
	v_mul_f32_e32 v131, 0xbfb8aa3b, v52
; DI unsigned pack2(float a, float b) { fl2_t f = {a, b}; bf2_t r = __builtin_convertvector(f, bf2_t); return __builtin_bit_cast(unsigned, r); }
; DI float sigmoidf_(float x) { return 1.f / (1.f + __expf(-x)); }
; DI void g1_phase(const P& p, int l, unsigned char* lds) {
;     ...
; #pragma unroll
;       for (int mt = 0; mt < 4; ++mt) {
;         const int wave2 = (2 * wm + (mt >> 1)) * 2 + wn2, mt2 = mt & 1;
; #pragma unroll
;         for (int nt = 0; nt < 2; ++nt)
; #pragma unroll
;           for (int g4 = 0; g4 < 4; ++g4) {
;             size_t idx = ((((((size_t)tm_ * 8 + tn2) * 8 + wave2) * 2 + mt2) * 2 + nt) * 4 + g4) * 64 + lane;
;             *(uint2*)(gf + idx * 4) = make_uint2(pack2(sigmoidf_(acc[mt][nt][4 * g4]), sigmoidf_(acc[mt][nt][4 * g4 + 1])),
;                                                  pack2(sigmoidf_(acc[mt][nt][4 * g4 + 2]), sigmoidf_(acc[mt][nt][4 * g4 + 3])));
;           }
	v_exp_f32_e32 v144, v131
	v_mul_f32_e32 v131, 0xbfb8aa3b, v53
	v_exp_f32_e32 v145, v131
	s_nop 0
	v_pk_add_f32 v[144:145], v[144:145], 1.0 op_sel_hi:[1,0]
	s_nop 0
	v_rcp_f32_e32 v141, v145
	s_nop 0
	v_fma_f32 v143, -v145, v141, 1.0
	v_fmac_f32_e32 v141, v143, v141
	v_fma_f32 v147, -v145, v141, 1.0
	v_fma_f32 v146, v147, v141, v141
	v_fma_f32 v131, -v145, v146, 1.0
	v_fma_f32 v131, v131, v141, v146
	v_rcp_f32_e32 v143, v144
	s_nop 0
	v_fma_f32 v145, -v144, v143, 1.0
	v_fmac_f32_e32 v143, v145, v143
	v_fma_f32 v147, -v144, v143, 1.0
	v_fma_f32 v146, v147, v143, v143
	v_fma_f32 v141, -v144, v146, 1.0
	v_fma_f32 v141, v141, v143, v146
	v_cvt_pk_bf16_f32 v143, v141, v131
	v_mul_f32_e32 v131, 0xbfb8aa3b, v54
	global_store_dwordx2 v[134:135], v[142:143], off offset:2048
	v_exp_f32_e32 v142, v131
	v_mul_f32_e32 v131, 0xbfb8aa3b, v55
	v_exp_f32_e32 v143, v131
	s_nop 0
	v_pk_add_f32 v[142:143], v[142:143], 1.0 op_sel_hi:[1,0]
	s_nop 0
	v_rcp_f32_e32 v141, v143
	s_nop 0
	v_fma_f32 v144, -v143, v141, 1.0
	v_fmac_f32_e32 v141, v144, v141
	v_fma_f32 v146, -v143, v141, 1.0
	v_fma_f32 v145, v146, v141, v141
	v_fma_f32 v131, -v143, v145, 1.0
	v_fma_f32 v131, v131, v141, v145
	v_rcp_f32_e32 v143, v142
	s_nop 0
	v_fma_f32 v144, -v142, v143, 1.0
	v_fmac_f32_e32 v143, v144, v143
	v_fma_f32 v146, -v142, v143, 1.0
	v_fma_f32 v145, v146, v143, v143
	v_fma_f32 v141, -v142, v145, 1.0
	v_fma_f32 v141, v141, v143, v145
	v_cvt_pk_bf16_f32 v142, v141, v131
	v_mul_f32_e32 v131, 0xbfb8aa3b, v56
	v_exp_f32_e32 v144, v131
	v_mul_f32_e32 v131, 0xbfb8aa3b, v57
	v_exp_f32_e32 v145, v131
	s_nop 0
	v_pk_add_f32 v[144:145], v[144:145], 1.0 op_sel_hi:[1,0]
	s_nop 0
	v_rcp_f32_e32 v141, v145
	s_nop 0
	v_fma_f32 v143, -v145, v141, 1.0
	v_fmac_f32_e32 v141, v143, v141
	v_fma_f32 v147, -v145, v141, 1.0
	v_fma_f32 v146, v147, v141, v141
	v_fma_f32 v131, -v145, v146, 1.0
	v_fma_f32 v131, v131, v141, v146
	v_rcp_f32_e32 v143, v144
	s_nop 0
	v_fma_f32 v145, -v144, v143, 1.0
	v_fmac_f32_e32 v143, v145, v143
	v_fma_f32 v147, -v144, v143, 1.0
	v_fma_f32 v146, v147, v143, v143
	v_fma_f32 v141, -v144, v146, 1.0
	v_fma_f32 v141, v141, v143, v146
	v_cvt_pk_bf16_f32 v143, v141, v131
	v_mul_f32_e32 v131, 0xbfb8aa3b, v58
	global_store_dwordx2 v[134:135], v[142:143], off offset:2560
	v_exp_f32_e32 v142, v131
	v_mul_f32_e32 v131, 0xbfb8aa3b, v59
	v_exp_f32_e32 v143, v131
	s_nop 0
	v_pk_add_f32 v[142:143], v[142:143], 1.0 op_sel_hi:[1,0]
	s_nop 0
	v_rcp_f32_e32 v141, v143
	s_nop 0
	v_fma_f32 v144, -v143, v141, 1.0
	v_fmac_f32_e32 v141, v144, v141
	v_fma_f32 v146, -v143, v141, 1.0
	v_fma_f32 v145, v146, v141, v141
	v_fma_f32 v131, -v143, v145, 1.0
	v_fma_f32 v131, v131, v141, v145
	v_rcp_f32_e32 v143, v142
	s_nop 0
	v_fma_f32 v144, -v142, v143, 1.0
	v_fmac_f32_e32 v143, v144, v143
	v_fma_f32 v146, -v142, v143, 1.0
	v_fma_f32 v145, v146, v143, v143
	v_fma_f32 v141, -v142, v145, 1.0
	v_fma_f32 v141, v141, v143, v145
	v_cvt_pk_bf16_f32 v142, v141, v131
	v_mul_f32_e32 v131, 0xbfb8aa3b, v60
	v_exp_f32_e32 v144, v131
	v_mul_f32_e32 v131, 0xbfb8aa3b, v61
	v_exp_f32_e32 v145, v131
	s_nop 0
	v_pk_add_f32 v[144:145], v[144:145], 1.0 op_sel_hi:[1,0]
	s_nop 0
	v_rcp_f32_e32 v141, v145
	s_nop 0
	v_fma_f32 v143, -v145, v141, 1.0
	v_fmac_f32_e32 v141, v143, v141
	v_fma_f32 v147, -v145, v141, 1.0
	v_fma_f32 v146, v147, v141, v141
	v_fma_f32 v131, -v145, v146, 1.0
	v_fma_f32 v131, v131, v141, v146
	v_rcp_f32_e32 v143, v144
	s_nop 0
	v_fma_f32 v145, -v144, v143, 1.0
	v_fmac_f32_e32 v143, v145, v143
	v_fma_f32 v147, -v144, v143, 1.0
	v_fma_f32 v146, v147, v143, v143
	v_fma_f32 v141, -v144, v146, 1.0
	v_fma_f32 v141, v141, v143, v146
	v_cvt_pk_bf16_f32 v143, v141, v131
	v_mul_f32_e32 v131, 0xbfb8aa3b, v62
	global_store_dwordx2 v[134:135], v[142:143], off offset:3072
	v_exp_f32_e32 v142, v131
	v_mul_f32_e32 v131, 0xbfb8aa3b, v63
	v_exp_f32_e32 v143, v131
	s_nop 0
	v_pk_add_f32 v[142:143], v[142:143], 1.0 op_sel_hi:[1,0]
	s_nop 0
	v_rcp_f32_e32 v141, v143
	s_nop 0
	v_fma_f32 v144, -v143, v141, 1.0
	v_fmac_f32_e32 v141, v144, v141
	v_fma_f32 v146, -v143, v141, 1.0
	v_fma_f32 v145, v146, v141, v141
	v_fma_f32 v131, -v143, v145, 1.0
	v_fma_f32 v131, v131, v141, v145
	v_rcp_f32_e32 v143, v142
	s_nop 0
	v_fma_f32 v144, -v142, v143, 1.0
	v_fmac_f32_e32 v143, v144, v143
	v_fma_f32 v146, -v142, v143, 1.0
	v_fma_f32 v145, v146, v143, v143
	v_fma_f32 v141, -v142, v145, 1.0
	v_fma_f32 v141, v141, v143, v145
	v_cvt_pk_bf16_f32 v142, v141, v131
	v_mul_f32_e32 v131, 0xbfb8aa3b, v64
	v_exp_f32_e32 v144, v131
	v_mul_f32_e32 v131, 0xbfb8aa3b, v65
	v_exp_f32_e32 v145, v131
	s_nop 0
	v_pk_add_f32 v[144:145], v[144:145], 1.0 op_sel_hi:[1,0]
	s_nop 0
	v_rcp_f32_e32 v141, v145
	s_nop 0
	v_fma_f32 v143, -v145, v141, 1.0
	v_fmac_f32_e32 v141, v143, v141
	v_fma_f32 v147, -v145, v141, 1.0
	v_fma_f32 v146, v147, v141, v141
	v_fma_f32 v131, -v145, v146, 1.0
	v_fma_f32 v131, v131, v141, v146
	v_rcp_f32_e32 v143, v144
	s_nop 0
	v_fma_f32 v145, -v144, v143, 1.0
	v_fmac_f32_e32 v143, v145, v143
	v_fma_f32 v147, -v144, v143, 1.0
	v_fma_f32 v146, v147, v143, v143
	v_fma_f32 v141, -v144, v146, 1.0
	v_fma_f32 v141, v141, v143, v146
	v_cvt_pk_bf16_f32 v143, v141, v131
	global_store_dwordx2 v[134:135], v[142:143], off offset:3584
	v_mul_f32_e32 v134, 0xbfb8aa3b, v66
	v_mul_f32_e32 v135, 0xbfb8aa3b, v67
	v_exp_f32_e32 v134, v134
	v_exp_f32_e32 v135, v135
	v_ashrrev_i32_e32 v131, 31, v130
	v_lshl_add_u64 v[130:131], v[178:179], 0, v[130:131]
	v_lshlrev_b64 v[130:131], 13, v[130:131]
	v_pk_add_f32 v[134:135], v[134:135], 1.0 op_sel_hi:[1,0]
	v_lshl_add_u64 v[130:131], s[0:1], 0, v[130:131]
	v_rcp_f32_e32 v142, v135
	v_lshl_add_u64 v[130:131], v[130:131], 0, v[132:133]
; DI unsigned pack2(float a, float b) { fl2_t f = {a, b}; bf2_t r = __builtin_convertvector(f, bf2_t); return __builtin_bit_cast(unsigned, r); }
; DI float sigmoidf_(float x) { return 1.f / (1.f + __expf(-x)); }
; DI void g1_phase(const P& p, int l, unsigned char* lds) {
;     ...
; #pragma unroll
;       for (int mt = 0; mt < 4; ++mt) {
;         const int wave2 = (2 * wm + (mt >> 1)) * 2 + wn2, mt2 = mt & 1;
; #pragma unroll
;         for (int nt = 0; nt < 2; ++nt)
; #pragma unroll
;           for (int g4 = 0; g4 < 4; ++g4) {
;             size_t idx = ((((((size_t)tm_ * 8 + tn2) * 8 + wave2) * 2 + mt2) * 2 + nt) * 4 + g4) * 64 + lane;
;             *(uint2*)(gf + idx * 4) = make_uint2(pack2(sigmoidf_(acc[mt][nt][4 * g4]), sigmoidf_(acc[mt][nt][4 * g4 + 1])),
;                                                  pack2(sigmoidf_(acc[mt][nt][4 * g4 + 2]), sigmoidf_(acc[mt][nt][4 * g4 + 3])));
;           }
	v_mul_f32_e32 v132, 0xbfb8aa3b, v70
	v_mul_f32_e32 v133, 0xbfb8aa3b, v71
	v_fma_f32 v143, -v135, v142, 1.0
	v_fmac_f32_e32 v142, v143, v142
	v_fma_f32 v145, -v135, v142, 1.0
	v_fma_f32 v144, v145, v142, v142
	v_fma_f32 v141, -v135, v144, 1.0
	v_fma_f32 v141, v141, v142, v144
	v_mov_b32_e32 v135, v141
	v_rcp_f32_e32 v142, v134
	v_exp_f32_e32 v132, v132
	v_exp_f32_e32 v133, v133
	v_fma_f32 v143, -v134, v142, 1.0
	v_fmac_f32_e32 v142, v143, v142
	v_fma_f32 v145, -v134, v142, 1.0
	v_fma_f32 v144, v145, v142, v142
	v_fma_f32 v141, -v134, v144, 1.0
	v_fma_f32 v141, v141, v142, v144
	v_cvt_pk_bf16_f32 v134, v141, v135
	v_mul_f32_e32 v135, 0xbfb8aa3b, v68
	v_exp_f32_e32 v142, v135
	v_mul_f32_e32 v135, 0xbfb8aa3b, v69
	v_exp_f32_e32 v143, v135
	v_pk_add_f32 v[132:133], v[132:133], 1.0 op_sel_hi:[1,0]
	v_pk_add_f32 v[142:143], v[142:143], 1.0 op_sel_hi:[1,0]
	s_nop 0
	v_rcp_f32_e32 v141, v143
	s_nop 0
	v_fma_f32 v144, -v143, v141, 1.0
	v_fmac_f32_e32 v141, v144, v141
	v_fma_f32 v146, -v143, v141, 1.0
	v_fma_f32 v145, v146, v141, v141
	v_fma_f32 v135, -v143, v145, 1.0
	v_fma_f32 v135, v135, v141, v145
	v_rcp_f32_e32 v143, v142
	s_nop 0
	v_fma_f32 v144, -v142, v143, 1.0
	v_fmac_f32_e32 v143, v144, v143
	v_fma_f32 v146, -v142, v143, 1.0
	v_fma_f32 v145, v146, v143, v143
	v_fma_f32 v141, -v142, v145, 1.0
	v_fma_f32 v141, v141, v143, v145
	v_cvt_pk_bf16_f32 v135, v141, v135
	global_store_dwordx2 v[130:131], v[134:135], off
	v_rcp_f32_e32 v135, v133
	s_nop 0
	v_fma_f32 v141, -v133, v135, 1.0
	v_fmac_f32_e32 v135, v141, v135
	v_fma_f32 v143, -v133, v135, 1.0
	v_fma_f32 v142, v143, v135, v135
	v_fma_f32 v134, -v133, v142, 1.0
	v_fma_f32 v134, v134, v135, v142
	v_mov_b32_e32 v133, v134
	v_rcp_f32_e32 v135, v132
	s_nop 0
	v_fma_f32 v141, -v132, v135, 1.0
	v_fmac_f32_e32 v135, v141, v135
	v_fma_f32 v143, -v132, v135, 1.0
	v_fma_f32 v142, v143, v135, v135
	v_fma_f32 v134, -v132, v142, 1.0
	v_fma_f32 v134, v134, v135, v142
	v_cvt_pk_bf16_f32 v132, v134, v133
	v_mul_f32_e32 v133, 0xbfb8aa3b, v72
	v_exp_f32_e32 v134, v133
	v_mul_f32_e32 v133, 0xbfb8aa3b, v73
	v_exp_f32_e32 v135, v133
	s_nop 0
	v_pk_add_f32 v[134:135], v[134:135], 1.0 op_sel_hi:[1,0]
	s_nop 0
	v_rcp_f32_e32 v141, v135
	s_nop 0
	v_fma_f32 v142, -v135, v141, 1.0
	v_fmac_f32_e32 v141, v142, v141
	v_fma_f32 v144, -v135, v141, 1.0
	v_fma_f32 v143, v144, v141, v141
	v_fma_f32 v133, -v135, v143, 1.0
	v_fma_f32 v133, v133, v141, v143
	v_rcp_f32_e32 v141, v134
	s_nop 0
	v_fma_f32 v142, -v134, v141, 1.0
	v_fmac_f32_e32 v141, v142, v141
	v_fma_f32 v144, -v134, v141, 1.0
	v_fma_f32 v143, v144, v141, v141
	v_fma_f32 v135, -v134, v143, 1.0
	v_fma_f32 v135, v135, v141, v143
	v_cvt_pk_bf16_f32 v133, v135, v133
	global_store_dwordx2 v[130:131], v[132:133], off offset:512
	v_mul_f32_e32 v132, 0xbfb8aa3b, v74
	v_mul_f32_e32 v133, 0xbfb8aa3b, v75
	v_exp_f32_e32 v132, v132
	v_exp_f32_e32 v133, v133
	s_nop 0
	v_pk_add_f32 v[132:133], v[132:133], 1.0 op_sel_hi:[1,0]
	s_nop 0
	v_rcp_f32_e32 v135, v133
	s_nop 0
	v_fma_f32 v141, -v133, v135, 1.0
	v_fmac_f32_e32 v135, v141, v135
	v_fma_f32 v143, -v133, v135, 1.0
	v_fma_f32 v142, v143, v135, v135
	v_fma_f32 v134, -v133, v142, 1.0
	v_fma_f32 v134, v134, v135, v142
	v_mov_b32_e32 v133, v134
	v_rcp_f32_e32 v135, v132
	s_nop 0
	v_fma_f32 v141, -v132, v135, 1.0
	v_fmac_f32_e32 v135, v141, v135
	v_fma_f32 v143, -v132, v135, 1.0
	v_fma_f32 v142, v143, v135, v135
	v_fma_f32 v134, -v132, v142, 1.0
	v_fma_f32 v134, v134, v135, v142
	v_cvt_pk_bf16_f32 v132, v134, v133
	v_mul_f32_e32 v133, 0xbfb8aa3b, v76
	v_exp_f32_e32 v134, v133
	v_mul_f32_e32 v133, 0xbfb8aa3b, v77
	v_exp_f32_e32 v135, v133
	s_nop 0
	v_pk_add_f32 v[134:135], v[134:135], 1.0 op_sel_hi:[1,0]
	s_nop 0
	v_rcp_f32_e32 v141, v135
	s_nop 0
	v_fma_f32 v142, -v135, v141, 1.0
	v_fmac_f32_e32 v141, v142, v141
	v_fma_f32 v144, -v135, v141, 1.0
	v_fma_f32 v143, v144, v141, v141
	v_fma_f32 v133, -v135, v143, 1.0
	v_fma_f32 v133, v133, v141, v143
	v_rcp_f32_e32 v141, v134
	s_nop 0
	v_fma_f32 v142, -v134, v141, 1.0
	v_fmac_f32_e32 v141, v142, v141
	v_fma_f32 v144, -v134, v141, 1.0
	v_fma_f32 v143, v144, v141, v141
	v_fma_f32 v135, -v134, v143, 1.0
	v_fma_f32 v135, v135, v141, v143
	v_cvt_pk_bf16_f32 v133, v135, v133
	global_store_dwordx2 v[130:131], v[132:133], off offset:1024
	v_mul_f32_e32 v132, 0xbfb8aa3b, v78
	v_mul_f32_e32 v133, 0xbfb8aa3b, v79
	v_exp_f32_e32 v132, v132
	v_exp_f32_e32 v133, v133
	s_nop 0
	v_pk_add_f32 v[132:133], v[132:133], 1.0 op_sel_hi:[1,0]
	s_nop 0
	v_rcp_f32_e32 v135, v133
	s_nop 0
	v_fma_f32 v141, -v133, v135, 1.0
	v_fmac_f32_e32 v135, v141, v135
	v_fma_f32 v143, -v133, v135, 1.0
	v_fma_f32 v142, v143, v135, v135
	v_fma_f32 v134, -v133, v142, 1.0
	v_fma_f32 v134, v134, v135, v142
	v_mov_b32_e32 v133, v134
	v_rcp_f32_e32 v135, v132
	s_nop 0
	v_fma_f32 v141, -v132, v135, 1.0
	v_fmac_f32_e32 v135, v141, v135
	v_fma_f32 v143, -v132, v135, 1.0
	v_fma_f32 v142, v143, v135, v135
	v_fma_f32 v134, -v132, v142, 1.0
	v_fma_f32 v134, v134, v135, v142
	v_cvt_pk_bf16_f32 v132, v134, v133
	v_mul_f32_e32 v133, 0xbfb8aa3b, v80
	v_exp_f32_e32 v134, v133
	v_mul_f32_e32 v133, 0xbfb8aa3b, v81
	v_exp_f32_e32 v135, v133
	s_nop 0
	v_pk_add_f32 v[134:135], v[134:135], 1.0 op_sel_hi:[1,0]
	s_nop 0
	v_rcp_f32_e32 v141, v135
	s_nop 0
	v_fma_f32 v142, -v135, v141, 1.0
	v_fmac_f32_e32 v141, v142, v141
	v_fma_f32 v144, -v135, v141, 1.0
	v_fma_f32 v143, v144, v141, v141
	v_fma_f32 v133, -v135, v143, 1.0
	v_fma_f32 v133, v133, v141, v143
	v_rcp_f32_e32 v141, v134
	s_nop 0
	v_fma_f32 v142, -v134, v141, 1.0
	v_fmac_f32_e32 v141, v142, v141
	v_fma_f32 v144, -v134, v141, 1.0
	v_fma_f32 v143, v144, v141, v141
	v_fma_f32 v135, -v134, v143, 1.0
; DI unsigned pack2(float a, float b) { fl2_t f = {a, b}; bf2_t r = __builtin_convertvector(f, bf2_t); return __builtin_bit_cast(unsigned, r); }
; DI float sigmoidf_(float x) { return 1.f / (1.f + __expf(-x)); }
; DI void g1_phase(const P& p, int l, unsigned char* lds) {
;     ...
; #pragma unroll
;       for (int mt = 0; mt < 4; ++mt) {
;         const int wave2 = (2 * wm + (mt >> 1)) * 2 + wn2, mt2 = mt & 1;
; #pragma unroll
;         for (int nt = 0; nt < 2; ++nt)
; #pragma unroll
;           for (int g4 = 0; g4 < 4; ++g4) {
;             size_t idx = ((((((size_t)tm_ * 8 + tn2) * 8 + wave2) * 2 + mt2) * 2 + nt) * 4 + g4) * 64 + lane;
;             *(uint2*)(gf + idx * 4) = make_uint2(pack2(sigmoidf_(acc[mt][nt][4 * g4]), sigmoidf_(acc[mt][nt][4 * g4 + 1])),
;                                                  pack2(sigmoidf_(acc[mt][nt][4 * g4 + 2]), sigmoidf_(acc[mt][nt][4 * g4 + 3])));
;           }
	v_fma_f32 v135, v135, v141, v143
	v_cvt_pk_bf16_f32 v133, v135, v133
	global_store_dwordx2 v[130:131], v[132:133], off offset:1536
	v_mul_f32_e32 v132, 0xbfb8aa3b, v82
	v_mul_f32_e32 v133, 0xbfb8aa3b, v83
	v_exp_f32_e32 v132, v132
	v_exp_f32_e32 v133, v133
	s_nop 0
	v_pk_add_f32 v[132:133], v[132:133], 1.0 op_sel_hi:[1,0]
	s_nop 0
	v_rcp_f32_e32 v135, v133
	s_nop 0
	v_fma_f32 v141, -v133, v135, 1.0
	v_fmac_f32_e32 v135, v141, v135
	v_fma_f32 v143, -v133, v135, 1.0
	v_fma_f32 v142, v143, v135, v135
	v_fma_f32 v134, -v133, v142, 1.0
	v_fma_f32 v134, v134, v135, v142
	v_mov_b32_e32 v133, v134
	v_rcp_f32_e32 v135, v132
	s_nop 0
	v_fma_f32 v141, -v132, v135, 1.0
	v_fmac_f32_e32 v135, v141, v135
	v_fma_f32 v143, -v132, v135, 1.0
	v_fma_f32 v142, v143, v135, v135
	v_fma_f32 v134, -v132, v142, 1.0
	v_fma_f32 v134, v134, v135, v142
	v_cvt_pk_bf16_f32 v132, v134, v133
	v_mul_f32_e32 v133, 0xbfb8aa3b, v84
	v_exp_f32_e32 v134, v133
	v_mul_f32_e32 v133, 0xbfb8aa3b, v85
	v_exp_f32_e32 v135, v133
	s_nop 0
	v_pk_add_f32 v[134:135], v[134:135], 1.0 op_sel_hi:[1,0]
	s_nop 0
	v_rcp_f32_e32 v141, v135
	s_nop 0
	v_fma_f32 v142, -v135, v141, 1.0
	v_fmac_f32_e32 v141, v142, v141
	v_fma_f32 v144, -v135, v141, 1.0
	v_fma_f32 v143, v144, v141, v141
	v_fma_f32 v133, -v135, v143, 1.0
	v_fma_f32 v133, v133, v141, v143
	v_rcp_f32_e32 v141, v134
	s_nop 0
	v_fma_f32 v142, -v134, v141, 1.0
	v_fmac_f32_e32 v141, v142, v141
	v_fma_f32 v144, -v134, v141, 1.0
	v_fma_f32 v143, v144, v141, v141
	v_fma_f32 v135, -v134, v143, 1.0
	v_fma_f32 v135, v135, v141, v143
	v_cvt_pk_bf16_f32 v133, v135, v133
	global_store_dwordx2 v[130:131], v[132:133], off offset:2048
	v_mul_f32_e32 v132, 0xbfb8aa3b, v86
	v_mul_f32_e32 v133, 0xbfb8aa3b, v87
	v_exp_f32_e32 v132, v132
	v_exp_f32_e32 v133, v133
	s_nop 0
	v_pk_add_f32 v[132:133], v[132:133], 1.0 op_sel_hi:[1,0]
	s_nop 0
	v_rcp_f32_e32 v135, v133
	s_nop 0
	v_fma_f32 v141, -v133, v135, 1.0
	v_fmac_f32_e32 v135, v141, v135
	v_fma_f32 v143, -v133, v135, 1.0
	v_fma_f32 v142, v143, v135, v135
	v_fma_f32 v134, -v133, v142, 1.0
	v_fma_f32 v134, v134, v135, v142
	v_mov_b32_e32 v133, v134
	v_rcp_f32_e32 v135, v132
	s_nop 0
	v_fma_f32 v141, -v132, v135, 1.0
	v_fmac_f32_e32 v135, v141, v135
	v_fma_f32 v143, -v132, v135, 1.0
	v_fma_f32 v142, v143, v135, v135
	v_fma_f32 v134, -v132, v142, 1.0
	v_fma_f32 v134, v134, v135, v142
	v_cvt_pk_bf16_f32 v132, v134, v133
	v_mul_f32_e32 v133, 0xbfb8aa3b, v88
	v_exp_f32_e32 v134, v133
	v_mul_f32_e32 v133, 0xbfb8aa3b, v89
	v_exp_f32_e32 v135, v133
	s_nop 0
	v_pk_add_f32 v[134:135], v[134:135], 1.0 op_sel_hi:[1,0]
	s_nop 0
	v_rcp_f32_e32 v141, v135
	s_nop 0
	v_fma_f32 v142, -v135, v141, 1.0
	v_fmac_f32_e32 v141, v142, v141
	v_fma_f32 v144, -v135, v141, 1.0
	v_fma_f32 v143, v144, v141, v141
	v_fma_f32 v133, -v135, v143, 1.0
	v_fma_f32 v133, v133, v141, v143
	v_rcp_f32_e32 v141, v134
	s_nop 0
	v_fma_f32 v142, -v134, v141, 1.0
	v_fmac_f32_e32 v141, v142, v141
	v_fma_f32 v144, -v134, v141, 1.0
	v_fma_f32 v143, v144, v141, v141
	v_fma_f32 v135, -v134, v143, 1.0
	v_fma_f32 v135, v135, v141, v143
	v_cvt_pk_bf16_f32 v133, v135, v133
	global_store_dwordx2 v[130:131], v[132:133], off offset:2560
	v_mul_f32_e32 v132, 0xbfb8aa3b, v90
	v_mul_f32_e32 v133, 0xbfb8aa3b, v91
	v_exp_f32_e32 v132, v132
	v_exp_f32_e32 v133, v133
	s_nop 0
	v_pk_add_f32 v[132:133], v[132:133], 1.0 op_sel_hi:[1,0]
	s_nop 0
	v_rcp_f32_e32 v135, v133
	s_nop 0
	v_fma_f32 v141, -v133, v135, 1.0
	v_fmac_f32_e32 v135, v141, v135
	v_fma_f32 v143, -v133, v135, 1.0
	v_fma_f32 v142, v143, v135, v135
	v_fma_f32 v134, -v133, v142, 1.0
	v_fma_f32 v134, v134, v135, v142
	v_mov_b32_e32 v133, v134
	v_rcp_f32_e32 v135, v132
	s_nop 0
	v_fma_f32 v141, -v132, v135, 1.0
	v_fmac_f32_e32 v135, v141, v135
	v_fma_f32 v143, -v132, v135, 1.0
	v_fma_f32 v142, v143, v135, v135
	v_fma_f32 v134, -v132, v142, 1.0
	v_fma_f32 v134, v134, v135, v142
	v_cvt_pk_bf16_f32 v132, v134, v133
	v_mul_f32_e32 v133, 0xbfb8aa3b, v92
	v_exp_f32_e32 v134, v133
	v_mul_f32_e32 v133, 0xbfb8aa3b, v93
	v_exp_f32_e32 v135, v133
	s_nop 0
	v_pk_add_f32 v[134:135], v[134:135], 1.0 op_sel_hi:[1,0]
	s_nop 0
	v_rcp_f32_e32 v141, v135
	s_nop 0
	v_fma_f32 v142, -v135, v141, 1.0
	v_fmac_f32_e32 v141, v142, v141
	v_fma_f32 v144, -v135, v141, 1.0
	v_fma_f32 v143, v144, v141, v141
	v_fma_f32 v133, -v135, v143, 1.0
	v_fma_f32 v133, v133, v141, v143
	v_rcp_f32_e32 v141, v134
	s_nop 0
	v_fma_f32 v142, -v134, v141, 1.0
	v_fmac_f32_e32 v141, v142, v141
	v_fma_f32 v144, -v134, v141, 1.0
	v_fma_f32 v143, v144, v141, v141
	v_fma_f32 v135, -v134, v143, 1.0
	v_fma_f32 v135, v135, v141, v143
	v_cvt_pk_bf16_f32 v133, v135, v133
	global_store_dwordx2 v[130:131], v[132:133], off offset:3072
	v_mul_f32_e32 v132, 0xbfb8aa3b, v94
	v_mul_f32_e32 v133, 0xbfb8aa3b, v95
	v_exp_f32_e32 v132, v132
	v_exp_f32_e32 v133, v133
	s_nop 0
	v_pk_add_f32 v[132:133], v[132:133], 1.0 op_sel_hi:[1,0]
	s_nop 0
	v_rcp_f32_e32 v135, v133
	s_nop 0
	v_fma_f32 v141, -v133, v135, 1.0
	v_fmac_f32_e32 v135, v141, v135
	v_fma_f32 v143, -v133, v135, 1.0
	v_fma_f32 v142, v143, v135, v135
	v_fma_f32 v134, -v133, v142, 1.0
	v_fma_f32 v134, v134, v135, v142
	v_mov_b32_e32 v133, v134
	v_rcp_f32_e32 v135, v132
	s_nop 0
	v_fma_f32 v141, -v132, v135, 1.0
	v_fmac_f32_e32 v135, v141, v135
	v_fma_f32 v143, -v132, v135, 1.0
	v_fma_f32 v142, v143, v135, v135
	v_fma_f32 v134, -v132, v142, 1.0
	v_fma_f32 v134, v134, v135, v142
	v_cvt_pk_bf16_f32 v132, v134, v133
	v_mul_f32_e32 v133, 0xbfb8aa3b, v96
	v_exp_f32_e32 v134, v133
	v_mul_f32_e32 v133, 0xbfb8aa3b, v97
	v_exp_f32_e32 v135, v133
	s_nop 0
	v_pk_add_f32 v[134:135], v[134:135], 1.0 op_sel_hi:[1,0]
	s_nop 0
	v_rcp_f32_e32 v141, v135
; DI unsigned pack2(float a, float b) { fl2_t f = {a, b}; bf2_t r = __builtin_convertvector(f, bf2_t); return __builtin_bit_cast(unsigned, r); }
; DI float sigmoidf_(float x) { return 1.f / (1.f + __expf(-x)); }
; DI void g1_phase(const P& p, int l, unsigned char* lds) {
;     ...
; #pragma unroll
;       for (int mt = 0; mt < 4; ++mt) {
;         const int wave2 = (2 * wm + (mt >> 1)) * 2 + wn2, mt2 = mt & 1;
; #pragma unroll
;         for (int nt = 0; nt < 2; ++nt)
; #pragma unroll
;           for (int g4 = 0; g4 < 4; ++g4) {
;             size_t idx = ((((((size_t)tm_ * 8 + tn2) * 8 + wave2) * 2 + mt2) * 2 + nt) * 4 + g4) * 64 + lane;
;             *(uint2*)(gf + idx * 4) = make_uint2(pack2(sigmoidf_(acc[mt][nt][4 * g4]), sigmoidf_(acc[mt][nt][4 * g4 + 1])),
;                                                  pack2(sigmoidf_(acc[mt][nt][4 * g4 + 2]), sigmoidf_(acc[mt][nt][4 * g4 + 3])));
;           }
	s_nop 0
	v_fma_f32 v142, -v135, v141, 1.0
	v_fmac_f32_e32 v141, v142, v141
	v_fma_f32 v144, -v135, v141, 1.0
	v_fma_f32 v143, v144, v141, v141
	v_fma_f32 v133, -v135, v143, 1.0
	v_fma_f32 v133, v133, v141, v143
	v_rcp_f32_e32 v141, v134
	s_nop 0
	v_fma_f32 v142, -v134, v141, 1.0
	v_fmac_f32_e32 v141, v142, v141
	v_fma_f32 v144, -v134, v141, 1.0
	v_fma_f32 v143, v144, v141, v141
	v_fma_f32 v135, -v134, v143, 1.0
	v_fma_f32 v135, v135, v141, v143
	v_cvt_pk_bf16_f32 v133, v135, v133
	global_store_dwordx2 v[130:131], v[132:133], off offset:3584
	v_mul_f32_e32 v132, 0xbfb8aa3b, v98
	v_mul_f32_e32 v133, 0xbfb8aa3b, v99
	v_exp_f32_e32 v132, v132
	v_exp_f32_e32 v133, v133
	s_nop 0
	v_pk_add_f32 v[132:133], v[132:133], 1.0 op_sel_hi:[1,0]
	s_nop 0
	v_rcp_f32_e32 v135, v133
	s_nop 0
	v_fma_f32 v141, -v133, v135, 1.0
	v_fmac_f32_e32 v135, v141, v135
	v_fma_f32 v143, -v133, v135, 1.0
	v_fma_f32 v142, v143, v135, v135
	v_fma_f32 v134, -v133, v142, 1.0
	v_fma_f32 v134, v134, v135, v142
	v_mov_b32_e32 v133, v134
	v_rcp_f32_e32 v135, v132
	s_nop 0
	v_fma_f32 v141, -v132, v135, 1.0
	v_fmac_f32_e32 v135, v141, v135
	v_fma_f32 v143, -v132, v135, 1.0
	v_fma_f32 v142, v143, v135, v135
	v_fma_f32 v134, -v132, v142, 1.0
	v_fma_f32 v134, v134, v135, v142
	v_cvt_pk_bf16_f32 v132, v134, v133
	v_mul_f32_e32 v133, 0xbfb8aa3b, v100
	v_exp_f32_e32 v134, v133
	v_mul_f32_e32 v133, 0xbfb8aa3b, v101
	v_exp_f32_e32 v135, v133
	s_nop 0
	v_pk_add_f32 v[134:135], v[134:135], 1.0 op_sel_hi:[1,0]
	s_nop 0
	v_rcp_f32_e32 v141, v135
	s_nop 0
	v_fma_f32 v142, -v135, v141, 1.0
	v_fmac_f32_e32 v141, v142, v141
	v_fma_f32 v144, -v135, v141, 1.0
	v_fma_f32 v143, v144, v141, v141
	v_fma_f32 v133, -v135, v143, 1.0
	v_fma_f32 v133, v133, v141, v143
	v_rcp_f32_e32 v141, v134
	s_nop 0
	v_fma_f32 v142, -v134, v141, 1.0
	v_fmac_f32_e32 v141, v142, v141
	v_fma_f32 v144, -v134, v141, 1.0
	v_fma_f32 v143, v144, v141, v141
	v_fma_f32 v135, -v134, v143, 1.0
	v_fma_f32 v135, v135, v141, v143
	v_add_co_u32_e32 v130, vcc, s46, v130
	v_cvt_pk_bf16_f32 v133, v135, v133
	s_nop 0
	v_addc_co_u32_e32 v131, vcc, 0, v131, vcc
	global_store_dwordx2 v[130:131], v[132:133], off
	v_mul_f32_e32 v132, 0xbfb8aa3b, v102
	v_mul_f32_e32 v133, 0xbfb8aa3b, v103
	v_exp_f32_e32 v132, v132
	v_exp_f32_e32 v133, v133
	s_nop 0
	v_pk_add_f32 v[132:133], v[132:133], 1.0 op_sel_hi:[1,0]
	s_nop 0
	v_rcp_f32_e32 v135, v133
	s_nop 0
	v_fma_f32 v141, -v133, v135, 1.0
	v_fmac_f32_e32 v135, v141, v135
	v_fma_f32 v143, -v133, v135, 1.0
	v_fma_f32 v142, v143, v135, v135
	v_fma_f32 v134, -v133, v142, 1.0
	v_fma_f32 v134, v134, v135, v142
	v_mov_b32_e32 v133, v134
	v_rcp_f32_e32 v135, v132
	s_nop 0
	v_fma_f32 v141, -v132, v135, 1.0
	v_fmac_f32_e32 v135, v141, v135
	v_fma_f32 v143, -v132, v135, 1.0
	v_fma_f32 v142, v143, v135, v135
	v_fma_f32 v134, -v132, v142, 1.0
	v_fma_f32 v134, v134, v135, v142
	v_cvt_pk_bf16_f32 v132, v134, v133
	v_mul_f32_e32 v133, 0xbfb8aa3b, v104
	v_exp_f32_e32 v134, v133
	v_mul_f32_e32 v133, 0xbfb8aa3b, v105
	v_exp_f32_e32 v135, v133
	s_nop 0
	v_pk_add_f32 v[134:135], v[134:135], 1.0 op_sel_hi:[1,0]
	s_nop 0
	v_rcp_f32_e32 v141, v135
	s_nop 0
	v_fma_f32 v142, -v135, v141, 1.0
	v_fmac_f32_e32 v141, v142, v141
	v_fma_f32 v144, -v135, v141, 1.0
	v_fma_f32 v143, v144, v141, v141
	v_fma_f32 v133, -v135, v143, 1.0
	v_fma_f32 v133, v133, v141, v143
	v_rcp_f32_e32 v141, v134
	s_nop 0
	v_fma_f32 v142, -v134, v141, 1.0
	v_fmac_f32_e32 v141, v142, v141
	v_fma_f32 v144, -v134, v141, 1.0
	v_fma_f32 v143, v144, v141, v141
	v_fma_f32 v135, -v134, v143, 1.0
	v_fma_f32 v135, v135, v141, v143
	v_cvt_pk_bf16_f32 v133, v135, v133
	global_store_dwordx2 v[130:131], v[132:133], off offset:512
	v_mul_f32_e32 v132, 0xbfb8aa3b, v106
	v_mul_f32_e32 v133, 0xbfb8aa3b, v107
	v_exp_f32_e32 v132, v132
	v_exp_f32_e32 v133, v133
	s_nop 0
	v_pk_add_f32 v[132:133], v[132:133], 1.0 op_sel_hi:[1,0]
	s_nop 0
	v_rcp_f32_e32 v135, v133
	s_nop 0
	v_fma_f32 v141, -v133, v135, 1.0
	v_fmac_f32_e32 v135, v141, v135
	v_fma_f32 v143, -v133, v135, 1.0
	v_fma_f32 v142, v143, v135, v135
	v_fma_f32 v134, -v133, v142, 1.0
	v_fma_f32 v134, v134, v135, v142
	v_mov_b32_e32 v133, v134
	v_rcp_f32_e32 v135, v132
	s_nop 0
	v_fma_f32 v141, -v132, v135, 1.0
	v_fmac_f32_e32 v135, v141, v135
	v_fma_f32 v143, -v132, v135, 1.0
	v_fma_f32 v142, v143, v135, v135
	v_fma_f32 v134, -v132, v142, 1.0
	v_fma_f32 v134, v134, v135, v142
	v_cvt_pk_bf16_f32 v132, v134, v133
	v_mul_f32_e32 v133, 0xbfb8aa3b, v108
	v_exp_f32_e32 v134, v133
	v_mul_f32_e32 v133, 0xbfb8aa3b, v109
	v_exp_f32_e32 v135, v133
	s_nop 0
	v_pk_add_f32 v[134:135], v[134:135], 1.0 op_sel_hi:[1,0]
	s_nop 0
	v_rcp_f32_e32 v141, v135
	s_nop 0
	v_fma_f32 v142, -v135, v141, 1.0
	v_fmac_f32_e32 v141, v142, v141
	v_fma_f32 v144, -v135, v141, 1.0
	v_fma_f32 v143, v144, v141, v141
	v_fma_f32 v133, -v135, v143, 1.0
	v_fma_f32 v133, v133, v141, v143
	v_rcp_f32_e32 v141, v134
	s_nop 0
	v_fma_f32 v142, -v134, v141, 1.0
	v_fmac_f32_e32 v141, v142, v141
	v_fma_f32 v144, -v134, v141, 1.0
	v_fma_f32 v143, v144, v141, v141
	v_fma_f32 v135, -v134, v143, 1.0
	v_fma_f32 v135, v135, v141, v143
	v_cvt_pk_bf16_f32 v133, v135, v133
	global_store_dwordx2 v[130:131], v[132:133], off offset:1024
	v_mul_f32_e32 v132, 0xbfb8aa3b, v110
	v_mul_f32_e32 v133, 0xbfb8aa3b, v111
	v_exp_f32_e32 v132, v132
	v_exp_f32_e32 v133, v133
	s_nop 0
	v_pk_add_f32 v[132:133], v[132:133], 1.0 op_sel_hi:[1,0]
	s_nop 0
	v_rcp_f32_e32 v135, v133
	s_nop 0
	v_fma_f32 v141, -v133, v135, 1.0
	v_fmac_f32_e32 v135, v141, v135
	v_fma_f32 v143, -v133, v135, 1.0
	v_fma_f32 v142, v143, v135, v135
	v_fma_f32 v134, -v133, v142, 1.0
	v_fma_f32 v134, v134, v135, v142
	v_mov_b32_e32 v133, v134
; DI unsigned pack2(float a, float b) { fl2_t f = {a, b}; bf2_t r = __builtin_convertvector(f, bf2_t); return __builtin_bit_cast(unsigned, r); }
; DI float sigmoidf_(float x) { return 1.f / (1.f + __expf(-x)); }
; DI void g1_phase(const P& p, int l, unsigned char* lds) {
;     ...
; #pragma unroll
;       for (int mt = 0; mt < 4; ++mt) {
;         const int wave2 = (2 * wm + (mt >> 1)) * 2 + wn2, mt2 = mt & 1;
; #pragma unroll
;         for (int nt = 0; nt < 2; ++nt)
; #pragma unroll
;           for (int g4 = 0; g4 < 4; ++g4) {
;             size_t idx = ((((((size_t)tm_ * 8 + tn2) * 8 + wave2) * 2 + mt2) * 2 + nt) * 4 + g4) * 64 + lane;
;             *(uint2*)(gf + idx * 4) = make_uint2(pack2(sigmoidf_(acc[mt][nt][4 * g4]), sigmoidf_(acc[mt][nt][4 * g4 + 1])),
;                                                  pack2(sigmoidf_(acc[mt][nt][4 * g4 + 2]), sigmoidf_(acc[mt][nt][4 * g4 + 3])));
;           }
	v_rcp_f32_e32 v135, v132
	s_nop 0
	v_fma_f32 v141, -v132, v135, 1.0
	v_fmac_f32_e32 v135, v141, v135
	v_fma_f32 v143, -v132, v135, 1.0
	v_fma_f32 v142, v143, v135, v135
	v_fma_f32 v134, -v132, v142, 1.0
	v_fma_f32 v134, v134, v135, v142
	v_cvt_pk_bf16_f32 v132, v134, v133
	v_mul_f32_e32 v133, 0xbfb8aa3b, v112
	v_exp_f32_e32 v134, v133
	v_mul_f32_e32 v133, 0xbfb8aa3b, v113
	v_exp_f32_e32 v135, v133
	s_nop 0
	v_pk_add_f32 v[134:135], v[134:135], 1.0 op_sel_hi:[1,0]
	s_nop 0
	v_rcp_f32_e32 v141, v135
	s_nop 0
	v_fma_f32 v142, -v135, v141, 1.0
	v_fmac_f32_e32 v141, v142, v141
	v_fma_f32 v144, -v135, v141, 1.0
	v_fma_f32 v143, v144, v141, v141
	v_fma_f32 v133, -v135, v143, 1.0
	v_fma_f32 v133, v133, v141, v143
	v_rcp_f32_e32 v141, v134
	s_nop 0
	v_fma_f32 v142, -v134, v141, 1.0
	v_fmac_f32_e32 v141, v142, v141
	v_fma_f32 v144, -v134, v141, 1.0
	v_fma_f32 v143, v144, v141, v141
	v_fma_f32 v135, -v134, v143, 1.0
	v_fma_f32 v135, v135, v141, v143
	v_cvt_pk_bf16_f32 v133, v135, v133
	global_store_dwordx2 v[130:131], v[132:133], off offset:1536
	v_mul_f32_e32 v132, 0xbfb8aa3b, v114
	v_mul_f32_e32 v133, 0xbfb8aa3b, v115
	v_exp_f32_e32 v132, v132
	v_exp_f32_e32 v133, v133
	s_nop 0
	v_pk_add_f32 v[132:133], v[132:133], 1.0 op_sel_hi:[1,0]
	s_nop 0
	v_rcp_f32_e32 v135, v133
	s_nop 0
	v_fma_f32 v141, -v133, v135, 1.0
	v_fmac_f32_e32 v135, v141, v135
	v_fma_f32 v143, -v133, v135, 1.0
	v_fma_f32 v142, v143, v135, v135
	v_fma_f32 v134, -v133, v142, 1.0
	v_fma_f32 v134, v134, v135, v142
	v_mov_b32_e32 v133, v134
	v_rcp_f32_e32 v135, v132
	s_nop 0
	v_fma_f32 v141, -v132, v135, 1.0
	v_fmac_f32_e32 v135, v141, v135
	v_fma_f32 v143, -v132, v135, 1.0
	v_fma_f32 v142, v143, v135, v135
	v_fma_f32 v134, -v132, v142, 1.0
	v_fma_f32 v134, v134, v135, v142
	v_cvt_pk_bf16_f32 v132, v134, v133
	v_mul_f32_e32 v133, 0xbfb8aa3b, v116
	v_exp_f32_e32 v134, v133
	v_mul_f32_e32 v133, 0xbfb8aa3b, v117
	v_exp_f32_e32 v135, v133
	s_nop 0
	v_pk_add_f32 v[134:135], v[134:135], 1.0 op_sel_hi:[1,0]
	s_nop 0
	v_rcp_f32_e32 v141, v135
	s_nop 0
	v_fma_f32 v142, -v135, v141, 1.0
	v_fmac_f32_e32 v141, v142, v141
	v_fma_f32 v144, -v135, v141, 1.0
	v_fma_f32 v143, v144, v141, v141
	v_fma_f32 v133, -v135, v143, 1.0
	v_fma_f32 v133, v133, v141, v143
	v_rcp_f32_e32 v141, v134
	s_nop 0
	v_fma_f32 v142, -v134, v141, 1.0
	v_fmac_f32_e32 v141, v142, v141
	v_fma_f32 v144, -v134, v141, 1.0
	v_fma_f32 v143, v144, v141, v141
	v_fma_f32 v135, -v134, v143, 1.0
	v_fma_f32 v135, v135, v141, v143
	v_cvt_pk_bf16_f32 v133, v135, v133
	global_store_dwordx2 v[130:131], v[132:133], off offset:2048
	v_mul_f32_e32 v132, 0xbfb8aa3b, v118
	v_mul_f32_e32 v133, 0xbfb8aa3b, v119
	v_exp_f32_e32 v132, v132
	v_exp_f32_e32 v133, v133
	s_nop 0
	v_pk_add_f32 v[132:133], v[132:133], 1.0 op_sel_hi:[1,0]
	s_nop 0
	v_rcp_f32_e32 v135, v133
	s_nop 0
	v_fma_f32 v141, -v133, v135, 1.0
	v_fmac_f32_e32 v135, v141, v135
	v_fma_f32 v143, -v133, v135, 1.0
	v_fma_f32 v142, v143, v135, v135
	v_fma_f32 v134, -v133, v142, 1.0
	v_fma_f32 v134, v134, v135, v142
	v_mov_b32_e32 v133, v134
	v_rcp_f32_e32 v135, v132
	s_nop 0
	v_fma_f32 v141, -v132, v135, 1.0
	v_fmac_f32_e32 v135, v141, v135
	v_fma_f32 v143, -v132, v135, 1.0
	v_fma_f32 v142, v143, v135, v135
	v_fma_f32 v134, -v132, v142, 1.0
	v_fma_f32 v134, v134, v135, v142
	v_cvt_pk_bf16_f32 v132, v134, v133
	v_mul_f32_e32 v133, 0xbfb8aa3b, v120
	v_exp_f32_e32 v134, v133
	v_mul_f32_e32 v133, 0xbfb8aa3b, v121
	v_exp_f32_e32 v135, v133
	s_nop 0
	v_pk_add_f32 v[134:135], v[134:135], 1.0 op_sel_hi:[1,0]
	s_nop 0
	v_rcp_f32_e32 v141, v135
	s_nop 0
	v_fma_f32 v142, -v135, v141, 1.0
; DI unsigned pack2(float a, float b) { fl2_t f = {a, b}; bf2_t r = __builtin_convertvector(f, bf2_t); return __builtin_bit_cast(unsigned, r); }
; DI float sigmoidf_(float x) { return 1.f / (1.f + __expf(-x)); }
; DI void g1_phase(const P& p, int l, unsigned char* lds) {
;     ...
; #pragma unroll
;       for (int mt = 0; mt < 4; ++mt) {
;         const int wave2 = (2 * wm + (mt >> 1)) * 2 + wn2, mt2 = mt & 1;
; #pragma unroll
;         for (int nt = 0; nt < 2; ++nt)
; #pragma unroll
;           for (int g4 = 0; g4 < 4; ++g4) {
;             size_t idx = ((((((size_t)tm_ * 8 + tn2) * 8 + wave2) * 2 + mt2) * 2 + nt) * 4 + g4) * 64 + lane;
;             *(uint2*)(gf + idx * 4) = make_uint2(pack2(sigmoidf_(acc[mt][nt][4 * g4]), sigmoidf_(acc[mt][nt][4 * g4 + 1])),
;                                                  pack2(sigmoidf_(acc[mt][nt][4 * g4 + 2]), sigmoidf_(acc[mt][nt][4 * g4 + 3])));
;           }
	v_fmac_f32_e32 v141, v142, v141
	v_fma_f32 v144, -v135, v141, 1.0
	v_fma_f32 v143, v144, v141, v141
	v_fma_f32 v133, -v135, v143, 1.0
	v_fma_f32 v133, v133, v141, v143
	v_rcp_f32_e32 v141, v134
	s_nop 0
	v_fma_f32 v142, -v134, v141, 1.0
	v_fmac_f32_e32 v141, v142, v141
	v_fma_f32 v144, -v134, v141, 1.0
	v_fma_f32 v143, v144, v141, v141
	v_fma_f32 v135, -v134, v143, 1.0
	v_fma_f32 v135, v135, v141, v143
	v_cvt_pk_bf16_f32 v133, v135, v133
	global_store_dwordx2 v[130:131], v[132:133], off offset:2560
	v_mul_f32_e32 v132, 0xbfb8aa3b, v122
	v_mul_f32_e32 v133, 0xbfb8aa3b, v123
	v_exp_f32_e32 v132, v132
	v_exp_f32_e32 v133, v133
	s_nop 0
	v_pk_add_f32 v[132:133], v[132:133], 1.0 op_sel_hi:[1,0]
	s_nop 0
	v_rcp_f32_e32 v135, v133
	s_nop 0
	v_fma_f32 v141, -v133, v135, 1.0
	v_fmac_f32_e32 v135, v141, v135
	v_fma_f32 v143, -v133, v135, 1.0
	v_fma_f32 v142, v143, v135, v135
	v_fma_f32 v134, -v133, v142, 1.0
	v_fma_f32 v134, v134, v135, v142
	v_mov_b32_e32 v133, v134
	v_rcp_f32_e32 v135, v132
	s_nop 0
	v_fma_f32 v141, -v132, v135, 1.0
	v_fmac_f32_e32 v135, v141, v135
	v_fma_f32 v143, -v132, v135, 1.0
	v_fma_f32 v142, v143, v135, v135
	v_fma_f32 v134, -v132, v142, 1.0
	v_fma_f32 v134, v134, v135, v142
	v_cvt_pk_bf16_f32 v132, v134, v133
	v_mul_f32_e32 v133, 0xbfb8aa3b, v124
	v_exp_f32_e32 v134, v133
	v_mul_f32_e32 v133, 0xbfb8aa3b, v125
	v_exp_f32_e32 v135, v133
	s_nop 0
	v_pk_add_f32 v[134:135], v[134:135], 1.0 op_sel_hi:[1,0]
	s_nop 0
	v_rcp_f32_e32 v141, v135
	s_nop 0
	v_fma_f32 v142, -v135, v141, 1.0
	v_fmac_f32_e32 v141, v142, v141
	v_fma_f32 v144, -v135, v141, 1.0
	v_fma_f32 v143, v144, v141, v141
	v_fma_f32 v133, -v135, v143, 1.0
	v_fma_f32 v133, v133, v141, v143
	v_rcp_f32_e32 v141, v134
	s_nop 0
	v_fma_f32 v142, -v134, v141, 1.0
	v_fmac_f32_e32 v141, v142, v141
	v_fma_f32 v144, -v134, v141, 1.0
	v_fma_f32 v143, v144, v141, v141
	v_fma_f32 v135, -v134, v143, 1.0
	v_fma_f32 v135, v135, v141, v143
	v_cvt_pk_bf16_f32 v133, v135, v133
	global_store_dwordx2 v[130:131], v[132:133], off offset:3072
	v_mul_f32_e32 v132, 0xbfb8aa3b, v126
	v_mul_f32_e32 v133, 0xbfb8aa3b, v127
	v_exp_f32_e32 v132, v132
	v_exp_f32_e32 v133, v133
	s_nop 0
	v_pk_add_f32 v[132:133], v[132:133], 1.0 op_sel_hi:[1,0]
	s_nop 0
	v_rcp_f32_e32 v135, v133
	s_nop 0
	v_fma_f32 v141, -v133, v135, 1.0
	v_fmac_f32_e32 v135, v141, v135
	v_fma_f32 v143, -v133, v135, 1.0
	v_fma_f32 v142, v143, v135, v135
	v_fma_f32 v134, -v133, v142, 1.0
	v_fma_f32 v134, v134, v135, v142
	v_mov_b32_e32 v133, v134
	v_rcp_f32_e32 v135, v132
	s_nop 0
	v_fma_f32 v141, -v132, v135, 1.0
	v_fmac_f32_e32 v135, v141, v135
	v_fma_f32 v143, -v132, v135, 1.0
	v_fma_f32 v142, v143, v135, v135
	v_fma_f32 v134, -v132, v142, 1.0
	v_fma_f32 v134, v134, v135, v142
	v_cvt_pk_bf16_f32 v132, v134, v133
	v_mul_f32_e32 v133, 0xbfb8aa3b, v128
	v_exp_f32_e32 v134, v133
	v_mul_f32_e32 v133, 0xbfb8aa3b, v129
	v_exp_f32_e32 v135, v133
	s_nop 0
	v_pk_add_f32 v[134:135], v[134:135], 1.0 op_sel_hi:[1,0]
	s_nop 0
	v_rcp_f32_e32 v141, v135
	s_nop 0
	v_fma_f32 v142, -v135, v141, 1.0
	v_fmac_f32_e32 v141, v142, v141
	v_fma_f32 v144, -v135, v141, 1.0
	v_fma_f32 v143, v144, v141, v141
	v_fma_f32 v133, -v135, v143, 1.0
	v_fma_f32 v133, v133, v141, v143
	v_rcp_f32_e32 v141, v134
	s_nop 0
	v_fma_f32 v142, -v134, v141, 1.0
	v_fmac_f32_e32 v141, v142, v141
	v_fma_f32 v144, -v134, v141, 1.0
	v_fma_f32 v143, v144, v141, v141
	v_fma_f32 v135, -v134, v143, 1.0
	v_fma_f32 v135, v135, v141, v143
	v_cvt_pk_bf16_f32 v133, v135, v133
	global_store_dwordx2 v[130:131], v[132:133], off offset:3584
	s_branch .LBB0_230

; DI u16 f2bf(float a) { return (u16)(pack2(a, 0.f) & 0xffffu); }
; DI float sigmoidf_(float x) { return 1.f / (1.f + __expf(-x)); }
; DI size_t boff(int row, int k, int K) { return ((size_t)(row >> 8) * (K >> 6) + (k >> 6)) * 16384 + (row & 255) * 64 + (k & 63); }
; DI void moe1_phase(const P& p, int l, unsigned char* lds) {
;     ...
;     const int j = (n0 >> 1) + wn * 32 + r;
;     const float* b1 = p.in[I_BE1] + (size_t)(l * 32 + e) * 2048;
;     const float bg = b1[2 * j], bl = b1[2 * j + 1];
;     u16* abase = ACT + boff(m0 + wm * 128 + 4 * hh, j, 1024);
; #pragma unroll
;     for (int mt = 0; mt < 4; ++mt)
; #pragma unroll
;       for (int i = 0; i < 16; ++i) {
;         float ug = fminf(acc[mt][0][i] + bg, 7.f);
;         float ul = fminf(fmaxf(acc[mt][1][i] + bl, -7.f), 7.f);
;         float a = ug * sigmoidf_(1.702f * ug) * (ul + 1.f);
;         abase[(mt * 32 + 8 * (i >> 2) + (i & 3)) * 64] = f2bf(a);
.LBB0_1415:
	s_or_b64 exec, exec, s[0:1]
	s_waitcnt vmcnt(3)
	v_lshl_or_b32 v136, s6, 7, v196
	v_add_u32_e32 v130, s52, v174
	v_or_b32_e32 v132, v136, v194
	v_ashrrev_i32_e32 v131, 31, v130
	v_readlane_b32 s20, v252, 0
	v_lshlrev_b64 v[130:131], 13, v[130:131]
	v_readlane_b32 s21, v252, 1
	v_lshlrev_b32_e32 v132, 1, v132
	v_ashrrev_i32_e32 v133, 31, v132
	v_lshl_add_u64 v[130:131], s[20:21], 0, v[130:131]
	v_lshl_add_u64 v[130:131], v[132:133], 2, v[130:131]
	global_load_dwordx2 v[130:131], v[130:131], off
	v_add_u32_e32 v132, s17, v197
	v_ashrrev_i32_e32 v132, 8, v132
	v_ashrrev_i32_e32 v133, 31, v132
	v_ashrrev_i32_e32 v134, 6, v136
	v_readlane_b32 s0, v253, 1
	v_ashrrev_i32_e32 v135, 31, v134
	v_lshlrev_b64 v[132:133], 19, v[132:133]
	v_readlane_b32 s1, v253, 2
	v_lshlrev_b64 v[134:135], 15, v[134:135]
	v_bitop3_b32 v136, v136, 63, v194 bitop3:0xc8
	v_lshl_add_u64 v[132:133], s[0:1], 0, v[132:133]
	v_lshl_add_u64 v[132:133], v[132:133], 0, v[134:135]
	v_lshlrev_b32_e32 v178, 1, v136
	v_mov_b32_e32 v173, v179
	v_lshl_add_u64 v[132:133], v[132:133], 0, v[172:173]
	v_lshl_add_u64 v[132:133], v[132:133], 0, v[178:179]
	v_readlane_b32 s22, v252, 2
	v_readlane_b32 s23, v252, 3
	v_readlane_b32 s24, v252, 4
	v_readlane_b32 s25, v252, 5
	v_readlane_b32 s26, v252, 6
	v_readlane_b32 s27, v252, 7
	s_waitcnt vmcnt(0)
	v_min_f32_e32 v150, v18, v19
	v_min3_f32 v150, v150, v20, v21
	v_min3_f32 v150, v150, v22, v23
	v_min3_f32 v150, v150, v24, v25
	v_min3_f32 v150, v150, v26, v27
	v_min3_f32 v150, v150, v28, v29
	v_min3_f32 v150, v150, v30, v31
	v_min3_f32 v150, v150, v32, v33
	v_min3_f32 v150, v150, v50, v51
	v_min3_f32 v150, v150, v52, v53
	v_min3_f32 v150, v150, v54, v55
	v_min3_f32 v150, v150, v56, v57
	v_min3_f32 v150, v150, v58, v59
	v_min3_f32 v150, v150, v60, v61
	v_min3_f32 v150, v150, v62, v63
	v_min3_f32 v150, v150, v64, v65
	v_min3_f32 v150, v150, v82, v83
	v_min3_f32 v150, v150, v84, v85
	v_min3_f32 v150, v150, v86, v87
	v_min3_f32 v150, v150, v88, v89
	v_min3_f32 v150, v150, v90, v91
	v_min3_f32 v150, v150, v92, v93
	v_min3_f32 v150, v150, v94, v95
	v_min3_f32 v150, v150, v96, v97
	v_min3_f32 v150, v150, v114, v115
	v_min3_f32 v150, v150, v116, v117
	v_min3_f32 v150, v150, v118, v119
	v_min3_f32 v150, v150, v120, v121
	v_min3_f32 v150, v150, v122, v123
	v_min3_f32 v150, v150, v124, v125
	v_min3_f32 v150, v150, v126, v127
	v_min3_f32 v150, v150, v128, v129
	v_add_f32_e32 v150, v150, v130
	v_mov_b32_e32 v151, 0xc20c0000
	s_nop 0
	v_cmp_nlt_f32_e32 vcc, v151, v150
	s_cbranch_vccnz .Lmoe1_epi_slow
	v_add_f32_e32 v114, v114, v130
	v_min_f32_e32 v114, 0x40e00000, v114
	v_mul_f32_e32 v134, 0x3fd9db23, v114
	v_mul_f32_e32 v134, 0xbfb8aa3b, v134
	v_exp_f32_e32 v134, v134
	v_add_f32_e32 v98, v98, v131
	v_med3_f32 v98, v98, s36, v225
	v_add_f32_e32 v98, 1.0, v98
	v_add_f32_e32 v134, 1.0, v134
	v_rcp_f32_e32 v136, v134
	v_add_f32_e32 v99, v99, v131
	v_med3_f32 v99, v99, s36, v225
	v_add_f32_e32 v99, 1.0, v99
	v_fma_f32 v137, -v134, v136, 1.0
	v_fmac_f32_e32 v136, v137, v136
	v_fma_f32 v139, -v134, v136, 1.0
	v_fma_f32 v138, v139, v136, v136
	v_fma_f32 v135, -v134, v138, 1.0
	v_fma_f32 v135, v135, v136, v138
	v_mul_f32_e32 v114, v114, v135
	v_mul_f32_e32 v98, v98, v114
	v_cvt_pk_bf16_f32 v98, v98, s0
	global_store_short v[132:133], v98, off
	v_add_f32_e32 v98, v115, v130
	v_min_f32_e32 v98, 0x40e00000, v98
	v_mul_f32_e32 v114, 0x3fd9db23, v98
	v_mul_f32_e32 v114, 0xbfb8aa3b, v114
	v_exp_f32_e32 v114, v114
	v_add_f32_e32 v82, v82, v130
	v_min_f32_e32 v82, 0x40e00000, v82
	v_add_f32_e32 v66, v66, v131
	v_add_f32_e32 v114, 1.0, v114
	v_rcp_f32_e32 v134, v114
	v_med3_f32 v66, v66, s36, v225
	v_add_f32_e32 v66, 1.0, v66
	v_add_f32_e32 v67, v67, v131
	v_fma_f32 v135, -v114, v134, 1.0
	v_fmac_f32_e32 v134, v135, v134
	v_fma_f32 v137, -v114, v134, 1.0
	v_fma_f32 v136, v137, v134, v134
	v_fma_f32 v115, -v114, v136, 1.0
	v_fma_f32 v115, v115, v134, v136
	v_mul_f32_e32 v98, v98, v115
	v_mul_f32_e32 v98, v99, v98
	v_cvt_pk_bf16_f32 v98, v98, s0
	global_store_short v[132:133], v98, off offset:128
	v_add_f32_e32 v98, v116, v130
	v_min_f32_e32 v98, 0x40e00000, v98
	v_add_f32_e32 v99, v100, v131
	v_mul_f32_e32 v100, 0x3fd9db23, v98
	v_mul_f32_e32 v100, 0xbfb8aa3b, v100
	v_exp_f32_e32 v100, v100
	v_med3_f32 v99, v99, s36, v225
	v_add_f32_e32 v99, 1.0, v99
	v_med3_f32 v67, v67, s36, v225
	v_add_f32_e32 v100, 1.0, v100
	v_rcp_f32_e32 v115, v100
	v_add_f32_e32 v67, 1.0, v67
	v_add_f32_e32 v50, v50, v130
	v_min_f32_e32 v50, 0x40e00000, v50
	v_fma_f32 v116, -v100, v115, 1.0
	v_fmac_f32_e32 v115, v116, v115
	v_fma_f32 v135, -v100, v115, 1.0
	v_fma_f32 v134, v135, v115, v115
	v_fma_f32 v114, -v100, v134, 1.0
	v_fma_f32 v114, v114, v115, v134
	v_mul_f32_e32 v98, v98, v114
	v_mul_f32_e32 v98, v99, v98
	v_cvt_pk_bf16_f32 v98, v98, s0
	global_store_short v[132:133], v98, off offset:256
	v_add_f32_e32 v98, v117, v130
	v_min_f32_e32 v98, 0x40e00000, v98
	v_mul_f32_e32 v100, 0x3fd9db23, v98
	v_mul_f32_e32 v100, 0xbfb8aa3b, v100
	v_exp_f32_e32 v100, v100
	v_add_f32_e32 v99, v101, v131
	v_med3_f32 v99, v99, s36, v225
	v_add_f32_e32 v99, 1.0, v99
	v_add_f32_e32 v100, 1.0, v100
	v_rcp_f32_e32 v114, v100
	v_add_f32_e32 v34, v34, v131
	v_med3_f32 v34, v34, s36, v225
	v_add_f32_e32 v34, 1.0, v34
	v_fma_f32 v115, -v100, v114, 1.0
	v_fmac_f32_e32 v114, v115, v114
	v_fma_f32 v117, -v100, v114, 1.0
	v_fma_f32 v116, v117, v114, v114
	v_fma_f32 v101, -v100, v116, 1.0
	v_fma_f32 v101, v101, v114, v116
	v_mul_f32_e32 v98, v98, v101
	v_mul_f32_e32 v98, v99, v98
	v_cvt_pk_bf16_f32 v98, v98, s0
	global_store_short v[132:133], v98, off offset:384
	v_add_f32_e32 v98, v118, v130
	v_min_f32_e32 v98, 0x40e00000, v98
; DI u16 f2bf(float a) { return (u16)(pack2(a, 0.f) & 0xffffu); }
; DI float sigmoidf_(float x) { return 1.f / (1.f + __expf(-x)); }
; DI void moe1_phase(const P& p, int l, unsigned char* lds) {
;     ...
;       for (int i = 0; i < 16; ++i) {
;         float ug = fminf(acc[mt][0][i] + bg, 7.f);
;         float ul = fminf(fmaxf(acc[mt][1][i] + bl, -7.f), 7.f);
;         float a = ug * sigmoidf_(1.702f * ug) * (ul + 1.f);
;         abase[(mt * 32 + 8 * (i >> 2) + (i & 3)) * 64] = f2bf(a);
	v_mul_f32_e32 v100, 0x3fd9db23, v98
	v_mul_f32_e32 v100, 0xbfb8aa3b, v100
	v_exp_f32_e32 v100, v100
	v_add_f32_e32 v99, v102, v131
	v_med3_f32 v99, v99, s36, v225
	v_add_f32_e32 v99, 1.0, v99
	v_add_f32_e32 v100, 1.0, v100
	v_rcp_f32_e32 v102, v100
	v_add_f32_e32 v35, v35, v131
	v_med3_f32 v35, v35, s36, v225
	v_add_f32_e32 v35, 1.0, v35
	v_fma_f32 v114, -v100, v102, 1.0
	v_fmac_f32_e32 v102, v114, v102
	v_fma_f32 v116, -v100, v102, 1.0
	v_fma_f32 v115, v116, v102, v102
	v_fma_f32 v101, -v100, v115, 1.0
	v_fma_f32 v101, v101, v102, v115
	v_mul_f32_e32 v98, v98, v101
	v_mul_f32_e32 v98, v99, v98
	v_cvt_pk_bf16_f32 v98, v98, s0
	global_store_short v[132:133], v98, off offset:1024
	v_add_f32_e32 v98, v119, v130
	v_min_f32_e32 v98, 0x40e00000, v98
	v_mul_f32_e32 v100, 0x3fd9db23, v98
	v_mul_f32_e32 v100, 0xbfb8aa3b, v100
	v_exp_f32_e32 v100, v100
	v_add_f32_e32 v99, v103, v131
	v_med3_f32 v99, v99, s36, v225
	v_add_f32_e32 v99, 1.0, v99
	v_add_f32_e32 v100, 1.0, v100
	v_rcp_f32_e32 v102, v100
	v_add_f32_e32 v18, v18, v130
	v_min_f32_e32 v18, 0x40e00000, v18
	v_add_f32_e32 v2, v2, v131
	v_fma_f32 v103, -v100, v102, 1.0
	v_fmac_f32_e32 v102, v103, v102
	v_fma_f32 v115, -v100, v102, 1.0
	v_fma_f32 v114, v115, v102, v102
	v_fma_f32 v101, -v100, v114, 1.0
	v_fma_f32 v101, v101, v102, v114
	v_mul_f32_e32 v98, v98, v101
	v_mul_f32_e32 v98, v99, v98
	v_cvt_pk_bf16_f32 v98, v98, s0
	global_store_short v[132:133], v98, off offset:1152
	v_add_f32_e32 v98, v120, v130
	v_min_f32_e32 v98, 0x40e00000, v98
	v_mul_f32_e32 v100, 0x3fd9db23, v98
	v_mul_f32_e32 v100, 0xbfb8aa3b, v100
	v_exp_f32_e32 v100, v100
	v_add_f32_e32 v99, v104, v131
	v_med3_f32 v99, v99, s36, v225
	v_add_f32_e32 v99, 1.0, v99
	v_add_f32_e32 v100, 1.0, v100
	v_rcp_f32_e32 v102, v100
	v_med3_f32 v2, v2, s36, v225
	v_add_f32_e32 v2, 1.0, v2
	v_add_f32_e32 v3, v3, v131
	v_fma_f32 v103, -v100, v102, 1.0
	v_fmac_f32_e32 v102, v103, v102
	v_fma_f32 v114, -v100, v102, 1.0
	v_fma_f32 v104, v114, v102, v102
	v_fma_f32 v101, -v100, v104, 1.0
	v_fma_f32 v101, v101, v102, v104
	v_mul_f32_e32 v98, v98, v101
	v_mul_f32_e32 v98, v99, v98
	v_cvt_pk_bf16_f32 v98, v98, s0
	global_store_short v[132:133], v98, off offset:1280
	v_add_f32_e32 v98, v121, v130
	v_min_f32_e32 v98, 0x40e00000, v98
	v_mul_f32_e32 v100, 0x3fd9db23, v98
	v_mul_f32_e32 v100, 0xbfb8aa3b, v100
	v_exp_f32_e32 v100, v100
	v_add_f32_e32 v99, v105, v131
	v_med3_f32 v99, v99, s36, v225
	v_add_f32_e32 v99, 1.0, v99
	v_add_f32_e32 v100, 1.0, v100
	v_rcp_f32_e32 v102, v100
	v_med3_f32 v3, v3, s36, v225
	v_add_f32_e32 v3, 1.0, v3
	v_fma_f32 v103, -v100, v102, 1.0
	v_fmac_f32_e32 v102, v103, v102
	v_fma_f32 v105, -v100, v102, 1.0
	v_fma_f32 v104, v105, v102, v102
	v_fma_f32 v101, -v100, v104, 1.0
	v_fma_f32 v101, v101, v102, v104
	v_mul_f32_e32 v98, v98, v101
	v_mul_f32_e32 v98, v99, v98
	v_cvt_pk_bf16_f32 v98, v98, s0
	global_store_short v[132:133], v98, off offset:1408
	v_add_f32_e32 v98, v122, v130
	v_min_f32_e32 v98, 0x40e00000, v98
	v_mul_f32_e32 v100, 0x3fd9db23, v98
	v_mul_f32_e32 v100, 0xbfb8aa3b, v100
	v_exp_f32_e32 v100, v100
	v_add_f32_e32 v99, v106, v131
	v_med3_f32 v99, v99, s36, v225
	v_add_f32_e32 v99, 1.0, v99
	v_add_f32_e32 v100, 1.0, v100
	v_rcp_f32_e32 v102, v100
	s_nop 0
	v_fma_f32 v103, -v100, v102, 1.0
	v_fmac_f32_e32 v102, v103, v102
	v_fma_f32 v105, -v100, v102, 1.0
	v_fma_f32 v104, v105, v102, v102
	v_fma_f32 v101, -v100, v104, 1.0
	v_fma_f32 v101, v101, v102, v104
	v_mul_f32_e32 v98, v98, v101
	v_mul_f32_e32 v98, v99, v98
	v_cvt_pk_bf16_f32 v98, v98, s0
	global_store_short v[132:133], v98, off offset:2048
	v_add_f32_e32 v98, v123, v130
	v_min_f32_e32 v98, 0x40e00000, v98
	v_mul_f32_e32 v100, 0x3fd9db23, v98
	v_mul_f32_e32 v100, 0xbfb8aa3b, v100
	v_exp_f32_e32 v100, v100
	v_add_f32_e32 v99, v107, v131
	v_med3_f32 v99, v99, s36, v225
	v_add_f32_e32 v99, 1.0, v99
	v_add_f32_e32 v100, 1.0, v100
	v_rcp_f32_e32 v102, v100
	s_nop 0
	v_fma_f32 v103, -v100, v102, 1.0
	v_fmac_f32_e32 v102, v103, v102
	v_fma_f32 v105, -v100, v102, 1.0
	v_fma_f32 v104, v105, v102, v102
	v_fma_f32 v101, -v100, v104, 1.0
	v_fma_f32 v101, v101, v102, v104
	v_mul_f32_e32 v98, v98, v101
	v_mul_f32_e32 v98, v99, v98
	v_cvt_pk_bf16_f32 v98, v98, s0
	global_store_short v[132:133], v98, off offset:2176
	v_add_f32_e32 v98, v124, v130
	v_min_f32_e32 v98, 0x40e00000, v98
	v_mul_f32_e32 v100, 0x3fd9db23, v98
	v_mul_f32_e32 v100, 0xbfb8aa3b, v100
	v_exp_f32_e32 v100, v100
	v_add_f32_e32 v99, v108, v131
	v_med3_f32 v99, v99, s36, v225
	v_add_f32_e32 v99, 1.0, v99
	v_add_f32_e32 v100, 1.0, v100
	v_rcp_f32_e32 v102, v100
	s_nop 0
	v_fma_f32 v103, -v100, v102, 1.0
	v_fmac_f32_e32 v102, v103, v102
	v_fma_f32 v105, -v100, v102, 1.0
	v_fma_f32 v104, v105, v102, v102
	v_fma_f32 v101, -v100, v104, 1.0
	v_fma_f32 v101, v101, v102, v104
	v_mul_f32_e32 v98, v98, v101
	v_mul_f32_e32 v98, v99, v98
	v_cvt_pk_bf16_f32 v98, v98, s0
	global_store_short v[132:133], v98, off offset:2304
	v_add_f32_e32 v98, v125, v130
	v_min_f32_e32 v98, 0x40e00000, v98
	v_mul_f32_e32 v100, 0x3fd9db23, v98
	v_mul_f32_e32 v100, 0xbfb8aa3b, v100
	v_exp_f32_e32 v100, v100
	v_add_f32_e32 v99, v109, v131
	v_med3_f32 v99, v99, s36, v225
	v_add_f32_e32 v99, 1.0, v99
	v_add_f32_e32 v100, 1.0, v100
	v_rcp_f32_e32 v102, v100
	s_nop 0
	v_fma_f32 v103, -v100, v102, 1.0
	v_fmac_f32_e32 v102, v103, v102
	v_fma_f32 v105, -v100, v102, 1.0
	v_fma_f32 v104, v105, v102, v102
	v_fma_f32 v101, -v100, v104, 1.0
	v_fma_f32 v101, v101, v102, v104
	v_mul_f32_e32 v98, v98, v101
	v_mul_f32_e32 v98, v99, v98
	v_cvt_pk_bf16_f32 v98, v98, s0
	global_store_short v[132:133], v98, off offset:2432
	v_add_f32_e32 v98, v126, v130
; DI u16 f2bf(float a) { return (u16)(pack2(a, 0.f) & 0xffffu); }
; DI float sigmoidf_(float x) { return 1.f / (1.f + __expf(-x)); }
; DI void moe1_phase(const P& p, int l, unsigned char* lds) {
;     ...
;     for (int mt = 0; mt < 4; ++mt)
; #pragma unroll
;       for (int i = 0; i < 16; ++i) {
;         float ug = fminf(acc[mt][0][i] + bg, 7.f);
;         float ul = fminf(fmaxf(acc[mt][1][i] + bl, -7.f), 7.f);
;         float a = ug * sigmoidf_(1.702f * ug) * (ul + 1.f);
;         abase[(mt * 32 + 8 * (i >> 2) + (i & 3)) * 64] = f2bf(a);
;       }
	v_min_f32_e32 v98, 0x40e00000, v98
	v_mul_f32_e32 v100, 0x3fd9db23, v98
	v_mul_f32_e32 v100, 0xbfb8aa3b, v100
	v_exp_f32_e32 v100, v100
	v_add_f32_e32 v99, v110, v131
	v_med3_f32 v99, v99, s36, v225
	v_add_f32_e32 v99, 1.0, v99
	v_add_f32_e32 v100, 1.0, v100
	v_rcp_f32_e32 v102, v100
	s_nop 0
	v_fma_f32 v103, -v100, v102, 1.0
	v_fmac_f32_e32 v102, v103, v102
	v_fma_f32 v105, -v100, v102, 1.0
	v_fma_f32 v104, v105, v102, v102
	v_fma_f32 v101, -v100, v104, 1.0
	v_fma_f32 v101, v101, v102, v104
	v_mul_f32_e32 v98, v98, v101
	v_mul_f32_e32 v98, v99, v98
	v_cvt_pk_bf16_f32 v98, v98, s0
	global_store_short v[132:133], v98, off offset:3072
	v_add_f32_e32 v98, v127, v130
	v_min_f32_e32 v98, 0x40e00000, v98
	v_mul_f32_e32 v100, 0x3fd9db23, v98
	v_mul_f32_e32 v100, 0xbfb8aa3b, v100
	v_exp_f32_e32 v100, v100
	v_add_f32_e32 v99, v111, v131
	v_med3_f32 v99, v99, s36, v225
	v_add_f32_e32 v99, 1.0, v99
	v_add_f32_e32 v100, 1.0, v100
	v_rcp_f32_e32 v102, v100
	s_nop 0
	v_fma_f32 v103, -v100, v102, 1.0
	v_fmac_f32_e32 v102, v103, v102
	v_fma_f32 v105, -v100, v102, 1.0
	v_fma_f32 v104, v105, v102, v102
	v_fma_f32 v101, -v100, v104, 1.0
	v_fma_f32 v101, v101, v102, v104
	v_mul_f32_e32 v98, v98, v101
	v_mul_f32_e32 v98, v99, v98
	v_cvt_pk_bf16_f32 v98, v98, s0
	global_store_short v[132:133], v98, off offset:3200
	v_add_f32_e32 v98, v128, v130
	v_min_f32_e32 v98, 0x40e00000, v98
	v_mul_f32_e32 v100, 0x3fd9db23, v98
	v_mul_f32_e32 v100, 0xbfb8aa3b, v100
	v_exp_f32_e32 v100, v100
	v_add_f32_e32 v99, v112, v131
	v_med3_f32 v99, v99, s36, v225
	v_add_f32_e32 v99, 1.0, v99
	v_add_f32_e32 v100, 1.0, v100
	v_rcp_f32_e32 v102, v100
	s_nop 0
	v_fma_f32 v103, -v100, v102, 1.0
	v_fmac_f32_e32 v102, v103, v102
	v_fma_f32 v105, -v100, v102, 1.0
	v_fma_f32 v104, v105, v102, v102
	v_fma_f32 v101, -v100, v104, 1.0
	v_fma_f32 v101, v101, v102, v104
	v_mul_f32_e32 v98, v98, v101
	v_mul_f32_e32 v98, v99, v98
	v_cvt_pk_bf16_f32 v98, v98, s0
	global_store_short v[132:133], v98, off offset:3328
	v_add_f32_e32 v98, v129, v130
	v_min_f32_e32 v98, 0x40e00000, v98
	v_mul_f32_e32 v100, 0x3fd9db23, v98
	v_mul_f32_e32 v100, 0xbfb8aa3b, v100
	v_exp_f32_e32 v100, v100
	v_add_f32_e32 v99, v113, v131
	v_med3_f32 v99, v99, s36, v225
	v_add_f32_e32 v99, 1.0, v99
	v_add_f32_e32 v100, 1.0, v100
	v_rcp_f32_e32 v102, v100
	s_nop 0
	v_fma_f32 v103, -v100, v102, 1.0
	v_fmac_f32_e32 v102, v103, v102
	v_fma_f32 v105, -v100, v102, 1.0
	v_fma_f32 v104, v105, v102, v102
	v_fma_f32 v101, -v100, v104, 1.0
	v_fma_f32 v101, v101, v102, v104
	v_mul_f32_e32 v98, v98, v101
	v_mul_f32_e32 v98, v99, v98
	v_cvt_pk_bf16_f32 v98, v98, s0
	global_store_short v[132:133], v98, off offset:3456
	v_mul_f32_e32 v98, 0x3fd9db23, v82
	v_mul_f32_e32 v98, 0xbfb8aa3b, v98
	v_exp_f32_e32 v98, v98
	s_nop 0
	v_add_f32_e32 v98, 1.0, v98
	v_rcp_f32_e32 v100, v98
	s_nop 0
	v_fma_f32 v101, -v98, v100, 1.0
	v_fmac_f32_e32 v100, v101, v100
	v_fma_f32 v103, -v98, v100, 1.0
	v_fma_f32 v102, v103, v100, v100
	v_fma_f32 v99, -v98, v102, 1.0
	v_fma_f32 v99, v99, v100, v102
	v_add_co_u32_e32 v100, vcc, s46, v132
	v_mul_f32_e32 v82, v82, v99
	s_nop 0
	v_addc_co_u32_e32 v101, vcc, 0, v133, vcc
	v_mul_f32_e32 v66, v66, v82
	v_add_co_u32_e32 v98, vcc, s91, v132
	v_cvt_pk_bf16_f32 v66, v66, s0
	s_nop 0
	v_addc_co_u32_e32 v99, vcc, 0, v133, vcc
	global_store_short v[98:99], v66, off offset:-4096
	v_add_f32_e32 v66, v83, v130
	v_min_f32_e32 v66, 0x40e00000, v66
	v_mul_f32_e32 v82, 0x3fd9db23, v66
	v_mul_f32_e32 v82, 0xbfb8aa3b, v82
	v_exp_f32_e32 v82, v82
	s_nop 0
	v_add_f32_e32 v82, 1.0, v82
	v_rcp_f32_e32 v102, v82
	s_nop 0
	v_fma_f32 v103, -v82, v102, 1.0
	v_fmac_f32_e32 v102, v103, v102
	v_fma_f32 v105, -v82, v102, 1.0
	v_fma_f32 v104, v105, v102, v102
	v_fma_f32 v83, -v82, v104, 1.0
	v_fma_f32 v83, v83, v102, v104
	v_mul_f32_e32 v66, v66, v83
	v_mul_f32_e32 v66, v67, v66
	v_cvt_pk_bf16_f32 v66, v66, s0
	global_store_short v[100:101], v66, off offset:128
	v_add_f32_e32 v66, v84, v130
	v_min_f32_e32 v66, 0x40e00000, v66
	v_add_f32_e32 v67, v68, v131
	v_mul_f32_e32 v68, 0x3fd9db23, v66
	v_mul_f32_e32 v68, 0xbfb8aa3b, v68
	v_exp_f32_e32 v68, v68
	v_med3_f32 v67, v67, s36, v225
	v_add_f32_e32 v67, 1.0, v67
	v_add_f32_e32 v68, 1.0, v68
	v_rcp_f32_e32 v83, v68
	s_nop 0
	v_fma_f32 v84, -v68, v83, 1.0
	v_fmac_f32_e32 v83, v84, v83
	v_fma_f32 v103, -v68, v83, 1.0
	v_fma_f32 v102, v103, v83, v83
	v_fma_f32 v82, -v68, v102, 1.0
	v_fma_f32 v82, v82, v83, v102
	v_mul_f32_e32 v66, v66, v82
	v_mul_f32_e32 v66, v67, v66
	v_cvt_pk_bf16_f32 v66, v66, s0
	global_store_short v[100:101], v66, off offset:256
	v_add_f32_e32 v66, v85, v130
	v_min_f32_e32 v66, 0x40e00000, v66
	v_mul_f32_e32 v68, 0x3fd9db23, v66
	v_mul_f32_e32 v68, 0xbfb8aa3b, v68
	v_exp_f32_e32 v68, v68
	v_add_f32_e32 v67, v69, v131
	v_med3_f32 v67, v67, s36, v225
	v_add_f32_e32 v67, 1.0, v67
	v_add_f32_e32 v68, 1.0, v68
	v_rcp_f32_e32 v82, v68
	s_nop 0
	v_fma_f32 v83, -v68, v82, 1.0
	v_fmac_f32_e32 v82, v83, v82
	v_fma_f32 v85, -v68, v82, 1.0
	v_fma_f32 v84, v85, v82, v82
	v_fma_f32 v69, -v68, v84, 1.0
	v_fma_f32 v69, v69, v82, v84
	v_mul_f32_e32 v66, v66, v69
	v_mul_f32_e32 v66, v67, v66
	v_cvt_pk_bf16_f32 v66, v66, s0
	global_store_short v[100:101], v66, off offset:384
	v_add_f32_e32 v66, v86, v130
	v_min_f32_e32 v66, 0x40e00000, v66
	v_mul_f32_e32 v68, 0x3fd9db23, v66
	v_mul_f32_e32 v68, 0xbfb8aa3b, v68
	v_exp_f32_e32 v68, v68
	v_add_f32_e32 v67, v70, v131
	v_med3_f32 v67, v67, s36, v225
	v_add_f32_e32 v67, 1.0, v67
	v_add_f32_e32 v68, 1.0, v68
	v_rcp_f32_e32 v70, v68
	s_nop 0
	v_fma_f32 v82, -v68, v70, 1.0
	v_fmac_f32_e32 v70, v82, v70
	v_fma_f32 v84, -v68, v70, 1.0
	v_fma_f32 v83, v84, v70, v70
; DI u16 f2bf(float a) { return (u16)(pack2(a, 0.f) & 0xffffu); }
; DI float sigmoidf_(float x) { return 1.f / (1.f + __expf(-x)); }
; DI void moe1_phase(const P& p, int l, unsigned char* lds) {
;     ...
;     for (int mt = 0; mt < 4; ++mt)
; #pragma unroll
;       for (int i = 0; i < 16; ++i) {
;         float ug = fminf(acc[mt][0][i] + bg, 7.f);
;         float ul = fminf(fmaxf(acc[mt][1][i] + bl, -7.f), 7.f);
;         float a = ug * sigmoidf_(1.702f * ug) * (ul + 1.f);
;         abase[(mt * 32 + 8 * (i >> 2) + (i & 3)) * 64] = f2bf(a);
;       }
	v_fma_f32 v69, -v68, v83, 1.0
	v_fma_f32 v69, v69, v70, v83
	v_mul_f32_e32 v66, v66, v69
	v_mul_f32_e32 v66, v67, v66
	v_cvt_pk_bf16_f32 v66, v66, s0
	global_store_short v[100:101], v66, off offset:1024
	v_add_f32_e32 v66, v87, v130
	v_min_f32_e32 v66, 0x40e00000, v66
	v_mul_f32_e32 v68, 0x3fd9db23, v66
	v_mul_f32_e32 v68, 0xbfb8aa3b, v68
	v_exp_f32_e32 v68, v68
	v_add_f32_e32 v67, v71, v131
	v_med3_f32 v67, v67, s36, v225
	v_add_f32_e32 v67, 1.0, v67
	v_add_f32_e32 v68, 1.0, v68
	v_rcp_f32_e32 v70, v68
	s_nop 0
	v_fma_f32 v71, -v68, v70, 1.0
	v_fmac_f32_e32 v70, v71, v70
	v_fma_f32 v83, -v68, v70, 1.0
	v_fma_f32 v82, v83, v70, v70
	v_fma_f32 v69, -v68, v82, 1.0
	v_fma_f32 v69, v69, v70, v82
	v_mul_f32_e32 v66, v66, v69
	v_mul_f32_e32 v66, v67, v66
	v_cvt_pk_bf16_f32 v66, v66, s0
	global_store_short v[100:101], v66, off offset:1152
	v_add_f32_e32 v66, v88, v130
	v_min_f32_e32 v66, 0x40e00000, v66
	v_mul_f32_e32 v68, 0x3fd9db23, v66
	v_mul_f32_e32 v68, 0xbfb8aa3b, v68
	v_exp_f32_e32 v68, v68
	v_add_f32_e32 v67, v72, v131
	v_med3_f32 v67, v67, s36, v225
	v_add_f32_e32 v67, 1.0, v67
	v_add_f32_e32 v68, 1.0, v68
	v_rcp_f32_e32 v70, v68
	s_nop 0
	v_fma_f32 v71, -v68, v70, 1.0
	v_fmac_f32_e32 v70, v71, v70
	v_fma_f32 v82, -v68, v70, 1.0
	v_fma_f32 v72, v82, v70, v70
	v_fma_f32 v69, -v68, v72, 1.0
	v_fma_f32 v69, v69, v70, v72
	v_mul_f32_e32 v66, v66, v69
	v_mul_f32_e32 v66, v67, v66
	v_cvt_pk_bf16_f32 v66, v66, s0
	global_store_short v[100:101], v66, off offset:1280
	v_add_f32_e32 v66, v89, v130
	v_min_f32_e32 v66, 0x40e00000, v66
	v_mul_f32_e32 v68, 0x3fd9db23, v66
	v_mul_f32_e32 v68, 0xbfb8aa3b, v68
	v_exp_f32_e32 v68, v68
	v_add_f32_e32 v67, v73, v131
	v_med3_f32 v67, v67, s36, v225
	v_add_f32_e32 v67, 1.0, v67
	v_add_f32_e32 v68, 1.0, v68
	v_rcp_f32_e32 v70, v68
	s_nop 0
	v_fma_f32 v71, -v68, v70, 1.0
	v_fmac_f32_e32 v70, v71, v70
	v_fma_f32 v73, -v68, v70, 1.0
	v_fma_f32 v72, v73, v70, v70
	v_fma_f32 v69, -v68, v72, 1.0
	v_fma_f32 v69, v69, v70, v72
	v_mul_f32_e32 v66, v66, v69
	v_mul_f32_e32 v66, v67, v66
	v_cvt_pk_bf16_f32 v66, v66, s0
	global_store_short v[100:101], v66, off offset:1408
	v_add_f32_e32 v66, v90, v130
	v_min_f32_e32 v66, 0x40e00000, v66
	v_mul_f32_e32 v68, 0x3fd9db23, v66
	v_mul_f32_e32 v68, 0xbfb8aa3b, v68
	v_exp_f32_e32 v68, v68
	v_add_f32_e32 v67, v74, v131
	v_med3_f32 v67, v67, s36, v225
	v_add_f32_e32 v67, 1.0, v67
	v_add_f32_e32 v68, 1.0, v68
	v_rcp_f32_e32 v70, v68
	s_nop 0
	v_fma_f32 v71, -v68, v70, 1.0
	v_fmac_f32_e32 v70, v71, v70
	v_fma_f32 v73, -v68, v70, 1.0
	v_fma_f32 v72, v73, v70, v70
	v_fma_f32 v69, -v68, v72, 1.0
	v_fma_f32 v69, v69, v70, v72
	v_mul_f32_e32 v66, v66, v69
	v_mul_f32_e32 v66, v67, v66
	v_cvt_pk_bf16_f32 v66, v66, s0
	global_store_short v[100:101], v66, off offset:2048
	v_add_f32_e32 v66, v91, v130
	v_min_f32_e32 v66, 0x40e00000, v66
	v_mul_f32_e32 v68, 0x3fd9db23, v66
	v_mul_f32_e32 v68, 0xbfb8aa3b, v68
	v_exp_f32_e32 v68, v68
	v_add_f32_e32 v67, v75, v131
	v_med3_f32 v67, v67, s36, v225
	v_add_f32_e32 v67, 1.0, v67
	v_add_f32_e32 v68, 1.0, v68
	v_rcp_f32_e32 v70, v68
	s_nop 0
	v_fma_f32 v71, -v68, v70, 1.0
	v_fmac_f32_e32 v70, v71, v70
	v_fma_f32 v73, -v68, v70, 1.0
	v_fma_f32 v72, v73, v70, v70
	v_fma_f32 v69, -v68, v72, 1.0
	v_fma_f32 v69, v69, v70, v72
	v_mul_f32_e32 v66, v66, v69
	v_mul_f32_e32 v66, v67, v66
	v_cvt_pk_bf16_f32 v66, v66, s0
	global_store_short v[100:101], v66, off offset:2176
	v_add_f32_e32 v66, v92, v130
	v_min_f32_e32 v66, 0x40e00000, v66
	v_mul_f32_e32 v68, 0x3fd9db23, v66
	v_mul_f32_e32 v68, 0xbfb8aa3b, v68
	v_exp_f32_e32 v68, v68
	v_add_f32_e32 v67, v76, v131
	v_med3_f32 v67, v67, s36, v225
	v_add_f32_e32 v67, 1.0, v67
	v_add_f32_e32 v68, 1.0, v68
	v_rcp_f32_e32 v70, v68
	s_nop 0
	v_fma_f32 v71, -v68, v70, 1.0
	v_fmac_f32_e32 v70, v71, v70
	v_fma_f32 v73, -v68, v70, 1.0
	v_fma_f32 v72, v73, v70, v70
	v_fma_f32 v69, -v68, v72, 1.0
	v_fma_f32 v69, v69, v70, v72
	v_mul_f32_e32 v66, v66, v69
	v_mul_f32_e32 v66, v67, v66
	v_cvt_pk_bf16_f32 v66, v66, s0
	global_store_short v[100:101], v66, off offset:2304
	v_add_f32_e32 v66, v93, v130
	v_min_f32_e32 v66, 0x40e00000, v66
	v_mul_f32_e32 v68, 0x3fd9db23, v66
	v_mul_f32_e32 v68, 0xbfb8aa3b, v68
	v_exp_f32_e32 v68, v68
	v_add_f32_e32 v67, v77, v131
	v_med3_f32 v67, v67, s36, v225
	v_add_f32_e32 v67, 1.0, v67
	v_add_f32_e32 v68, 1.0, v68
	v_rcp_f32_e32 v70, v68
	s_nop 0
	v_fma_f32 v71, -v68, v70, 1.0
	v_fmac_f32_e32 v70, v71, v70
	v_fma_f32 v73, -v68, v70, 1.0
	v_fma_f32 v72, v73, v70, v70
	v_fma_f32 v69, -v68, v72, 1.0
	v_fma_f32 v69, v69, v70, v72
	v_mul_f32_e32 v66, v66, v69
	v_mul_f32_e32 v66, v67, v66
	v_cvt_pk_bf16_f32 v66, v66, s0
	global_store_short v[100:101], v66, off offset:2432
	v_add_f32_e32 v66, v94, v130
	v_min_f32_e32 v66, 0x40e00000, v66
	v_mul_f32_e32 v68, 0x3fd9db23, v66
	v_mul_f32_e32 v68, 0xbfb8aa3b, v68
	v_exp_f32_e32 v68, v68
	v_add_f32_e32 v67, v78, v131
	v_med3_f32 v67, v67, s36, v225
	v_add_f32_e32 v67, 1.0, v67
	v_add_f32_e32 v68, 1.0, v68
	v_rcp_f32_e32 v70, v68
	s_nop 0
	v_fma_f32 v71, -v68, v70, 1.0
	v_fmac_f32_e32 v70, v71, v70
	v_fma_f32 v73, -v68, v70, 1.0
	v_fma_f32 v72, v73, v70, v70
	v_fma_f32 v69, -v68, v72, 1.0
	v_fma_f32 v69, v69, v70, v72
	v_mul_f32_e32 v66, v66, v69
	v_mul_f32_e32 v66, v67, v66
	v_cvt_pk_bf16_f32 v66, v66, s0
	global_store_short v[100:101], v66, off offset:3072
	v_add_f32_e32 v66, v95, v130
	v_min_f32_e32 v66, 0x40e00000, v66
	v_mul_f32_e32 v68, 0x3fd9db23, v66
	v_mul_f32_e32 v68, 0xbfb8aa3b, v68
	v_exp_f32_e32 v68, v68
	v_add_f32_e32 v67, v79, v131
	v_med3_f32 v67, v67, s36, v225
	v_add_f32_e32 v67, 1.0, v67
	v_add_f32_e32 v68, 1.0, v68
	v_rcp_f32_e32 v70, v68
; DI u16 f2bf(float a) { return (u16)(pack2(a, 0.f) & 0xffffu); }
; DI float sigmoidf_(float x) { return 1.f / (1.f + __expf(-x)); }
; DI void moe1_phase(const P& p, int l, unsigned char* lds) {
;     ...
;     for (int mt = 0; mt < 4; ++mt)
; #pragma unroll
;       for (int i = 0; i < 16; ++i) {
;         float ug = fminf(acc[mt][0][i] + bg, 7.f);
;         float ul = fminf(fmaxf(acc[mt][1][i] + bl, -7.f), 7.f);
;         float a = ug * sigmoidf_(1.702f * ug) * (ul + 1.f);
;         abase[(mt * 32 + 8 * (i >> 2) + (i & 3)) * 64] = f2bf(a);
;       }
	s_nop 0
	v_fma_f32 v71, -v68, v70, 1.0
	v_fmac_f32_e32 v70, v71, v70
	v_fma_f32 v73, -v68, v70, 1.0
	v_fma_f32 v72, v73, v70, v70
	v_fma_f32 v69, -v68, v72, 1.0
	v_fma_f32 v69, v69, v70, v72
	v_mul_f32_e32 v66, v66, v69
	v_mul_f32_e32 v66, v67, v66
	v_cvt_pk_bf16_f32 v66, v66, s0
	global_store_short v[100:101], v66, off offset:3200
	v_add_f32_e32 v66, v96, v130
	v_min_f32_e32 v66, 0x40e00000, v66
	v_mul_f32_e32 v68, 0x3fd9db23, v66
	v_mul_f32_e32 v68, 0xbfb8aa3b, v68
	v_exp_f32_e32 v68, v68
	v_add_f32_e32 v67, v80, v131
	v_med3_f32 v67, v67, s36, v225
	v_add_f32_e32 v67, 1.0, v67
	v_add_f32_e32 v68, 1.0, v68
	v_rcp_f32_e32 v70, v68
	s_nop 0
	v_fma_f32 v71, -v68, v70, 1.0
	v_fmac_f32_e32 v70, v71, v70
	v_fma_f32 v73, -v68, v70, 1.0
	v_fma_f32 v72, v73, v70, v70
	v_fma_f32 v69, -v68, v72, 1.0
	v_fma_f32 v69, v69, v70, v72
	v_mul_f32_e32 v66, v66, v69
	v_mul_f32_e32 v66, v67, v66
	v_cvt_pk_bf16_f32 v66, v66, s0
	global_store_short v[100:101], v66, off offset:3328
	v_add_f32_e32 v66, v97, v130
	v_min_f32_e32 v66, 0x40e00000, v66
	v_mul_f32_e32 v68, 0x3fd9db23, v66
	v_mul_f32_e32 v68, 0xbfb8aa3b, v68
	v_exp_f32_e32 v68, v68
	v_add_f32_e32 v67, v81, v131
	v_med3_f32 v67, v67, s36, v225
	v_add_f32_e32 v67, 1.0, v67
	v_add_f32_e32 v68, 1.0, v68
	v_rcp_f32_e32 v70, v68
	s_nop 0
	v_fma_f32 v71, -v68, v70, 1.0
	v_fmac_f32_e32 v70, v71, v70
	v_fma_f32 v73, -v68, v70, 1.0
	v_fma_f32 v72, v73, v70, v70
	v_fma_f32 v69, -v68, v72, 1.0
	v_fma_f32 v69, v69, v70, v72
	v_mul_f32_e32 v66, v66, v69
	v_mul_f32_e32 v66, v67, v66
	v_cvt_pk_bf16_f32 v66, v66, s0
	global_store_short v[100:101], v66, off offset:3456
	v_mul_f32_e32 v66, 0x3fd9db23, v50
	v_mul_f32_e32 v66, 0xbfb8aa3b, v66
	v_exp_f32_e32 v66, v66
	s_nop 0
	v_add_f32_e32 v66, 1.0, v66
	v_rcp_f32_e32 v68, v66
	s_nop 0
	v_fma_f32 v69, -v66, v68, 1.0
	v_fmac_f32_e32 v68, v69, v68
	v_fma_f32 v71, -v66, v68, 1.0
	v_fma_f32 v70, v71, v68, v68
	v_fma_f32 v67, -v66, v70, 1.0
	v_fma_f32 v67, v67, v68, v70
	v_mul_f32_e32 v50, v50, v67
	v_mul_f32_e32 v34, v34, v50
	v_cvt_pk_bf16_f32 v34, v34, s0
	global_store_short v[98:99], v34, off
	v_add_f32_e32 v34, v51, v130
	v_min_f32_e32 v34, 0x40e00000, v34
	v_mul_f32_e32 v50, 0x3fd9db23, v34
	v_mul_f32_e32 v50, 0xbfb8aa3b, v50
	v_exp_f32_e32 v50, v50
	s_nop 0
	v_add_f32_e32 v50, 1.0, v50
	v_rcp_f32_e32 v66, v50
	s_nop 0
	v_fma_f32 v67, -v50, v66, 1.0
	v_fmac_f32_e32 v66, v67, v66
	v_fma_f32 v69, -v50, v66, 1.0
	v_fma_f32 v68, v69, v66, v66
	v_fma_f32 v51, -v50, v68, 1.0
	v_fma_f32 v51, v51, v66, v68
	v_mul_f32_e32 v34, v34, v51
	v_mul_f32_e32 v34, v35, v34
	v_cvt_pk_bf16_f32 v34, v34, s0
	global_store_short v[98:99], v34, off offset:128
	v_add_f32_e32 v34, v52, v130
	v_min_f32_e32 v34, 0x40e00000, v34
	v_add_f32_e32 v35, v36, v131
	v_mul_f32_e32 v36, 0x3fd9db23, v34
	v_mul_f32_e32 v36, 0xbfb8aa3b, v36
	v_exp_f32_e32 v36, v36
	v_med3_f32 v35, v35, s36, v225
	v_add_f32_e32 v35, 1.0, v35
	v_add_f32_e32 v36, 1.0, v36
	v_rcp_f32_e32 v51, v36
	s_nop 0
	v_fma_f32 v52, -v36, v51, 1.0
	v_fmac_f32_e32 v51, v52, v51
	v_fma_f32 v67, -v36, v51, 1.0
	v_fma_f32 v66, v67, v51, v51
	v_fma_f32 v50, -v36, v66, 1.0
	v_fma_f32 v50, v50, v51, v66
	v_mul_f32_e32 v34, v34, v50
	v_mul_f32_e32 v34, v35, v34
	v_cvt_pk_bf16_f32 v34, v34, s0
	global_store_short v[98:99], v34, off offset:256
	v_add_f32_e32 v34, v53, v130
	v_min_f32_e32 v34, 0x40e00000, v34
	v_mul_f32_e32 v36, 0x3fd9db23, v34
	v_mul_f32_e32 v36, 0xbfb8aa3b, v36
	v_exp_f32_e32 v36, v36
	v_add_f32_e32 v35, v37, v131
	v_med3_f32 v35, v35, s36, v225
	v_add_f32_e32 v35, 1.0, v35
	v_add_f32_e32 v36, 1.0, v36
	v_rcp_f32_e32 v50, v36
	s_nop 0
	v_fma_f32 v51, -v36, v50, 1.0
	v_fmac_f32_e32 v50, v51, v50
	v_fma_f32 v53, -v36, v50, 1.0
	v_fma_f32 v52, v53, v50, v50
	v_fma_f32 v37, -v36, v52, 1.0
	v_fma_f32 v37, v37, v50, v52
	v_mul_f32_e32 v34, v34, v37
	v_mul_f32_e32 v34, v35, v34
	v_cvt_pk_bf16_f32 v34, v34, s0
	global_store_short v[98:99], v34, off offset:384
	v_add_f32_e32 v34, v54, v130
	v_min_f32_e32 v34, 0x40e00000, v34
	v_mul_f32_e32 v36, 0x3fd9db23, v34
	v_mul_f32_e32 v36, 0xbfb8aa3b, v36
	v_exp_f32_e32 v36, v36
	v_add_f32_e32 v35, v38, v131
	v_med3_f32 v35, v35, s36, v225
	v_add_f32_e32 v35, 1.0, v35
	v_add_f32_e32 v36, 1.0, v36
	v_rcp_f32_e32 v38, v36
	s_nop 0
	v_fma_f32 v50, -v36, v38, 1.0
	v_fmac_f32_e32 v38, v50, v38
	v_fma_f32 v52, -v36, v38, 1.0
	v_fma_f32 v51, v52, v38, v38
	v_fma_f32 v37, -v36, v51, 1.0
	v_fma_f32 v37, v37, v38, v51
	v_mul_f32_e32 v34, v34, v37
	v_mul_f32_e32 v34, v35, v34
	v_cvt_pk_bf16_f32 v34, v34, s0
	global_store_short v[98:99], v34, off offset:1024
	v_add_f32_e32 v34, v55, v130
	v_min_f32_e32 v34, 0x40e00000, v34
	v_mul_f32_e32 v36, 0x3fd9db23, v34
	v_mul_f32_e32 v36, 0xbfb8aa3b, v36
	v_exp_f32_e32 v36, v36
	v_add_f32_e32 v35, v39, v131
	v_med3_f32 v35, v35, s36, v225
	v_add_f32_e32 v35, 1.0, v35
	v_add_f32_e32 v36, 1.0, v36
	v_rcp_f32_e32 v38, v36
	s_nop 0
	v_fma_f32 v39, -v36, v38, 1.0
	v_fmac_f32_e32 v38, v39, v38
	v_fma_f32 v51, -v36, v38, 1.0
	v_fma_f32 v50, v51, v38, v38
	v_fma_f32 v37, -v36, v50, 1.0
	v_fma_f32 v37, v37, v38, v50
	v_mul_f32_e32 v34, v34, v37
	v_mul_f32_e32 v34, v35, v34
	v_cvt_pk_bf16_f32 v34, v34, s0
	global_store_short v[98:99], v34, off offset:1152
	v_add_f32_e32 v34, v56, v130
	v_min_f32_e32 v34, 0x40e00000, v34
	v_mul_f32_e32 v36, 0x3fd9db23, v34
	v_mul_f32_e32 v36, 0xbfb8aa3b, v36
	v_exp_f32_e32 v36, v36
	v_add_f32_e32 v35, v40, v131
	v_med3_f32 v35, v35, s36, v225
	v_add_f32_e32 v35, 1.0, v35
	v_add_f32_e32 v36, 1.0, v36
	v_rcp_f32_e32 v38, v36
	s_nop 0
	v_fma_f32 v39, -v36, v38, 1.0
	v_fmac_f32_e32 v38, v39, v38
	v_fma_f32 v50, -v36, v38, 1.0
	v_fma_f32 v40, v50, v38, v38
; DI u16 f2bf(float a) { return (u16)(pack2(a, 0.f) & 0xffffu); }
; DI float sigmoidf_(float x) { return 1.f / (1.f + __expf(-x)); }
; DI void moe1_phase(const P& p, int l, unsigned char* lds) {
;     ...
;     for (int mt = 0; mt < 4; ++mt)
; #pragma unroll
;       for (int i = 0; i < 16; ++i) {
;         float ug = fminf(acc[mt][0][i] + bg, 7.f);
;         float ul = fminf(fmaxf(acc[mt][1][i] + bl, -7.f), 7.f);
;         float a = ug * sigmoidf_(1.702f * ug) * (ul + 1.f);
;         abase[(mt * 32 + 8 * (i >> 2) + (i & 3)) * 64] = f2bf(a);
;       }
	v_fma_f32 v37, -v36, v40, 1.0
	v_fma_f32 v37, v37, v38, v40
	v_mul_f32_e32 v34, v34, v37
	v_mul_f32_e32 v34, v35, v34
	v_cvt_pk_bf16_f32 v34, v34, s0
	global_store_short v[98:99], v34, off offset:1280
	v_add_f32_e32 v34, v57, v130
	v_min_f32_e32 v34, 0x40e00000, v34
	v_mul_f32_e32 v36, 0x3fd9db23, v34
	v_mul_f32_e32 v36, 0xbfb8aa3b, v36
	v_exp_f32_e32 v36, v36
	v_add_f32_e32 v35, v41, v131
	v_med3_f32 v35, v35, s36, v225
	v_add_f32_e32 v35, 1.0, v35
	v_add_f32_e32 v36, 1.0, v36
	v_rcp_f32_e32 v38, v36
	s_nop 0
	v_fma_f32 v39, -v36, v38, 1.0
	v_fmac_f32_e32 v38, v39, v38
	v_fma_f32 v41, -v36, v38, 1.0
	v_fma_f32 v40, v41, v38, v38
	v_fma_f32 v37, -v36, v40, 1.0
	v_fma_f32 v37, v37, v38, v40
	v_mul_f32_e32 v34, v34, v37
	v_mul_f32_e32 v34, v35, v34
	v_cvt_pk_bf16_f32 v34, v34, s0
	global_store_short v[98:99], v34, off offset:1408
	v_add_f32_e32 v34, v58, v130
	v_min_f32_e32 v34, 0x40e00000, v34
	v_mul_f32_e32 v36, 0x3fd9db23, v34
	v_mul_f32_e32 v36, 0xbfb8aa3b, v36
	v_exp_f32_e32 v36, v36
	v_add_f32_e32 v35, v42, v131
	v_med3_f32 v35, v35, s36, v225
	v_add_f32_e32 v35, 1.0, v35
	v_add_f32_e32 v36, 1.0, v36
	v_rcp_f32_e32 v38, v36
	s_nop 0
	v_fma_f32 v39, -v36, v38, 1.0
	v_fmac_f32_e32 v38, v39, v38
	v_fma_f32 v41, -v36, v38, 1.0
	v_fma_f32 v40, v41, v38, v38
	v_fma_f32 v37, -v36, v40, 1.0
	v_fma_f32 v37, v37, v38, v40
	v_mul_f32_e32 v34, v34, v37
	v_mul_f32_e32 v34, v35, v34
	v_cvt_pk_bf16_f32 v34, v34, s0
	global_store_short v[98:99], v34, off offset:2048
	v_add_f32_e32 v34, v59, v130
	v_min_f32_e32 v34, 0x40e00000, v34
	v_mul_f32_e32 v36, 0x3fd9db23, v34
	v_mul_f32_e32 v36, 0xbfb8aa3b, v36
	v_exp_f32_e32 v36, v36
	v_add_f32_e32 v35, v43, v131
	v_med3_f32 v35, v35, s36, v225
	v_add_f32_e32 v35, 1.0, v35
	v_add_f32_e32 v36, 1.0, v36
	v_rcp_f32_e32 v38, v36
	s_nop 0
	v_fma_f32 v39, -v36, v38, 1.0
	v_fmac_f32_e32 v38, v39, v38
	v_fma_f32 v41, -v36, v38, 1.0
	v_fma_f32 v40, v41, v38, v38
	v_fma_f32 v37, -v36, v40, 1.0
	v_fma_f32 v37, v37, v38, v40
	v_mul_f32_e32 v34, v34, v37
	v_mul_f32_e32 v34, v35, v34
	v_cvt_pk_bf16_f32 v34, v34, s0
	global_store_short v[98:99], v34, off offset:2176
	v_add_f32_e32 v34, v60, v130
	v_min_f32_e32 v34, 0x40e00000, v34
	v_mul_f32_e32 v36, 0x3fd9db23, v34
	v_mul_f32_e32 v36, 0xbfb8aa3b, v36
	v_exp_f32_e32 v36, v36
	v_add_f32_e32 v35, v44, v131
	v_med3_f32 v35, v35, s36, v225
	v_add_f32_e32 v35, 1.0, v35
	v_add_f32_e32 v36, 1.0, v36
	v_rcp_f32_e32 v38, v36
	s_nop 0
	v_fma_f32 v39, -v36, v38, 1.0
	v_fmac_f32_e32 v38, v39, v38
	v_fma_f32 v41, -v36, v38, 1.0
	v_fma_f32 v40, v41, v38, v38
	v_fma_f32 v37, -v36, v40, 1.0
	v_fma_f32 v37, v37, v38, v40
	v_mul_f32_e32 v34, v34, v37
	v_mul_f32_e32 v34, v35, v34
	v_cvt_pk_bf16_f32 v34, v34, s0
	global_store_short v[98:99], v34, off offset:2304
	v_add_f32_e32 v34, v61, v130
	v_min_f32_e32 v34, 0x40e00000, v34
	v_mul_f32_e32 v36, 0x3fd9db23, v34
	v_mul_f32_e32 v36, 0xbfb8aa3b, v36
	v_exp_f32_e32 v36, v36
	v_add_f32_e32 v35, v45, v131
	v_med3_f32 v35, v35, s36, v225
	v_add_f32_e32 v35, 1.0, v35
	v_add_f32_e32 v36, 1.0, v36
	v_rcp_f32_e32 v38, v36
	s_nop 0
	v_fma_f32 v39, -v36, v38, 1.0
	v_fmac_f32_e32 v38, v39, v38
	v_fma_f32 v41, -v36, v38, 1.0
	v_fma_f32 v40, v41, v38, v38
	v_fma_f32 v37, -v36, v40, 1.0
	v_fma_f32 v37, v37, v38, v40
	v_mul_f32_e32 v34, v34, v37
	v_mul_f32_e32 v34, v35, v34
	v_cvt_pk_bf16_f32 v34, v34, s0
	global_store_short v[98:99], v34, off offset:2432
	v_add_f32_e32 v34, v62, v130
	v_min_f32_e32 v34, 0x40e00000, v34
	v_mul_f32_e32 v36, 0x3fd9db23, v34
	v_mul_f32_e32 v36, 0xbfb8aa3b, v36
	v_exp_f32_e32 v36, v36
	v_add_f32_e32 v35, v46, v131
	v_med3_f32 v35, v35, s36, v225
	v_add_f32_e32 v35, 1.0, v35
	v_add_f32_e32 v36, 1.0, v36
	v_rcp_f32_e32 v38, v36
	s_nop 0
	v_fma_f32 v39, -v36, v38, 1.0
	v_fmac_f32_e32 v38, v39, v38
	v_fma_f32 v41, -v36, v38, 1.0
	v_fma_f32 v40, v41, v38, v38
	v_fma_f32 v37, -v36, v40, 1.0
	v_fma_f32 v37, v37, v38, v40
	v_mul_f32_e32 v34, v34, v37
	v_mul_f32_e32 v34, v35, v34
	v_cvt_pk_bf16_f32 v34, v34, s0
	global_store_short v[98:99], v34, off offset:3072
	v_add_f32_e32 v34, v63, v130
	v_min_f32_e32 v34, 0x40e00000, v34
	v_mul_f32_e32 v36, 0x3fd9db23, v34
	v_mul_f32_e32 v36, 0xbfb8aa3b, v36
	v_exp_f32_e32 v36, v36
	v_add_f32_e32 v35, v47, v131
	v_med3_f32 v35, v35, s36, v225
	v_add_f32_e32 v35, 1.0, v35
	v_add_f32_e32 v36, 1.0, v36
	v_rcp_f32_e32 v38, v36
	s_nop 0
	v_fma_f32 v39, -v36, v38, 1.0
	v_fmac_f32_e32 v38, v39, v38
	v_fma_f32 v41, -v36, v38, 1.0
	v_fma_f32 v40, v41, v38, v38
	v_fma_f32 v37, -v36, v40, 1.0
	v_fma_f32 v37, v37, v38, v40
	v_mul_f32_e32 v34, v34, v37
	v_mul_f32_e32 v34, v35, v34
	v_cvt_pk_bf16_f32 v34, v34, s0
	global_store_short v[98:99], v34, off offset:3200
	v_add_f32_e32 v34, v64, v130
	v_min_f32_e32 v34, 0x40e00000, v34
	v_mul_f32_e32 v36, 0x3fd9db23, v34
	v_mul_f32_e32 v36, 0xbfb8aa3b, v36
	v_exp_f32_e32 v36, v36
	v_add_f32_e32 v35, v48, v131
	v_med3_f32 v35, v35, s36, v225
	v_add_f32_e32 v35, 1.0, v35
	v_add_f32_e32 v36, 1.0, v36
	v_rcp_f32_e32 v38, v36
	s_nop 0
	v_fma_f32 v39, -v36, v38, 1.0
	v_fmac_f32_e32 v38, v39, v38
	v_fma_f32 v41, -v36, v38, 1.0
	v_fma_f32 v40, v41, v38, v38
	v_fma_f32 v37, -v36, v40, 1.0
	v_fma_f32 v37, v37, v38, v40
	v_mul_f32_e32 v34, v34, v37
	v_mul_f32_e32 v34, v35, v34
	v_cvt_pk_bf16_f32 v34, v34, s0
	global_store_short v[98:99], v34, off offset:3328
	v_add_f32_e32 v34, v65, v130
	v_min_f32_e32 v34, 0x40e00000, v34
	v_mul_f32_e32 v36, 0x3fd9db23, v34
	v_mul_f32_e32 v36, 0xbfb8aa3b, v36
	v_exp_f32_e32 v36, v36
	v_add_f32_e32 v35, v49, v131
	v_med3_f32 v35, v35, s36, v225
	v_add_f32_e32 v35, 1.0, v35
	v_add_f32_e32 v36, 1.0, v36
	v_rcp_f32_e32 v38, v36
	s_nop 0
; DI u16 f2bf(float a) { return (u16)(pack2(a, 0.f) & 0xffffu); }
; DI float sigmoidf_(float x) { return 1.f / (1.f + __expf(-x)); }
; DI void moe1_phase(const P& p, int l, unsigned char* lds) {
;     ...
;     for (int mt = 0; mt < 4; ++mt)
; #pragma unroll
;       for (int i = 0; i < 16; ++i) {
;         float ug = fminf(acc[mt][0][i] + bg, 7.f);
;         float ul = fminf(fmaxf(acc[mt][1][i] + bl, -7.f), 7.f);
;         float a = ug * sigmoidf_(1.702f * ug) * (ul + 1.f);
;         abase[(mt * 32 + 8 * (i >> 2) + (i & 3)) * 64] = f2bf(a);
;       }
	v_fma_f32 v39, -v36, v38, 1.0
	v_fmac_f32_e32 v38, v39, v38
	v_fma_f32 v41, -v36, v38, 1.0
	v_fma_f32 v40, v41, v38, v38
	v_fma_f32 v37, -v36, v40, 1.0
	v_fma_f32 v37, v37, v38, v40
	v_mul_f32_e32 v34, v34, v37
	v_mul_f32_e32 v34, v35, v34
	v_cvt_pk_bf16_f32 v34, v34, s0
	global_store_short v[98:99], v34, off offset:3456
	v_mul_f32_e32 v34, 0x3fd9db23, v18
	v_mul_f32_e32 v34, 0xbfb8aa3b, v34
	v_exp_f32_e32 v34, v34
	s_nop 0
	v_add_f32_e32 v34, 1.0, v34
	v_rcp_f32_e32 v36, v34
	s_nop 0
	v_fma_f32 v37, -v34, v36, 1.0
	v_fmac_f32_e32 v36, v37, v36
	v_fma_f32 v39, -v34, v36, 1.0
	v_fma_f32 v38, v39, v36, v36
	v_fma_f32 v35, -v34, v38, 1.0
	v_fma_f32 v35, v35, v36, v38
	v_mul_f32_e32 v18, v18, v35
	v_mul_f32_e32 v2, v2, v18
	v_cvt_pk_bf16_f32 v2, v2, s0
	s_movk_i32 s0, 0x3000
	v_add_co_u32_e32 v34, vcc, s0, v132
	s_nop 1
	v_addc_co_u32_e32 v35, vcc, 0, v133, vcc
	global_store_short v[34:35], v2, off
	v_add_f32_e32 v2, v19, v130
	v_min_f32_e32 v2, 0x40e00000, v2
	v_mul_f32_e32 v18, 0x3fd9db23, v2
	v_mul_f32_e32 v18, 0xbfb8aa3b, v18
	v_exp_f32_e32 v18, v18
	s_nop 0
	v_add_f32_e32 v18, 1.0, v18
	v_rcp_f32_e32 v36, v18
	s_nop 0
	v_fma_f32 v37, -v18, v36, 1.0
	v_fmac_f32_e32 v36, v37, v36
	v_fma_f32 v39, -v18, v36, 1.0
	v_fma_f32 v38, v39, v36, v36
	v_fma_f32 v19, -v18, v38, 1.0
	v_fma_f32 v19, v19, v36, v38
	v_mul_f32_e32 v2, v2, v19
	v_mul_f32_e32 v2, v3, v2
	v_cvt_pk_bf16_f32 v2, v2, s0
	global_store_short v[34:35], v2, off offset:128
	v_add_f32_e32 v2, v20, v130
	v_min_f32_e32 v2, 0x40e00000, v2
	v_add_f32_e32 v3, v4, v131
	v_mul_f32_e32 v4, 0x3fd9db23, v2
	v_mul_f32_e32 v4, 0xbfb8aa3b, v4
	v_exp_f32_e32 v4, v4
	v_med3_f32 v3, v3, s36, v225
	v_add_f32_e32 v3, 1.0, v3
	v_add_f32_e32 v4, 1.0, v4
	v_rcp_f32_e32 v19, v4
	s_nop 0
	v_fma_f32 v20, -v4, v19, 1.0
	v_fmac_f32_e32 v19, v20, v19
	v_fma_f32 v37, -v4, v19, 1.0
	v_fma_f32 v36, v37, v19, v19
	v_fma_f32 v18, -v4, v36, 1.0
	v_fma_f32 v18, v18, v19, v36
	v_mul_f32_e32 v2, v2, v18
	v_mul_f32_e32 v2, v3, v2
	v_cvt_pk_bf16_f32 v2, v2, s0
	global_store_short v[34:35], v2, off offset:256
	v_add_f32_e32 v2, v21, v130
	v_min_f32_e32 v2, 0x40e00000, v2
	v_mul_f32_e32 v4, 0x3fd9db23, v2
	v_mul_f32_e32 v4, 0xbfb8aa3b, v4
	v_exp_f32_e32 v4, v4
	v_add_f32_e32 v3, v5, v131
	v_med3_f32 v3, v3, s36, v225
	v_add_f32_e32 v3, 1.0, v3
	v_add_f32_e32 v4, 1.0, v4
	v_rcp_f32_e32 v18, v4
	s_nop 0
	v_fma_f32 v19, -v4, v18, 1.0
	v_fmac_f32_e32 v18, v19, v18
	v_fma_f32 v21, -v4, v18, 1.0
	v_fma_f32 v20, v21, v18, v18
	v_fma_f32 v5, -v4, v20, 1.0
	v_fma_f32 v5, v5, v18, v20
	v_mul_f32_e32 v2, v2, v5
	v_mul_f32_e32 v2, v3, v2
	v_cvt_pk_bf16_f32 v2, v2, s0
	global_store_short v[34:35], v2, off offset:384
	v_add_f32_e32 v2, v22, v130
	v_min_f32_e32 v2, 0x40e00000, v2
	v_mul_f32_e32 v4, 0x3fd9db23, v2
	v_mul_f32_e32 v4, 0xbfb8aa3b, v4
	v_exp_f32_e32 v4, v4
	v_add_f32_e32 v3, v6, v131
	v_med3_f32 v3, v3, s36, v225
	v_add_f32_e32 v3, 1.0, v3
	v_add_f32_e32 v4, 1.0, v4
	v_rcp_f32_e32 v6, v4
	s_nop 0
	v_fma_f32 v18, -v4, v6, 1.0
	v_fmac_f32_e32 v6, v18, v6
	v_fma_f32 v20, -v4, v6, 1.0
	v_fma_f32 v19, v20, v6, v6
	v_fma_f32 v5, -v4, v19, 1.0
	v_fma_f32 v5, v5, v6, v19
	v_mul_f32_e32 v2, v2, v5
	v_mul_f32_e32 v2, v3, v2
	v_cvt_pk_bf16_f32 v2, v2, s0
	global_store_short v[34:35], v2, off offset:1024
	v_add_f32_e32 v2, v23, v130
	v_min_f32_e32 v2, 0x40e00000, v2
	v_mul_f32_e32 v4, 0x3fd9db23, v2
	v_mul_f32_e32 v4, 0xbfb8aa3b, v4
	v_exp_f32_e32 v4, v4
	v_add_f32_e32 v3, v7, v131
	v_med3_f32 v3, v3, s36, v225
	v_add_f32_e32 v3, 1.0, v3
	v_add_f32_e32 v4, 1.0, v4
	v_rcp_f32_e32 v6, v4
	s_nop 0
	v_fma_f32 v7, -v4, v6, 1.0
	v_fmac_f32_e32 v6, v7, v6
	v_fma_f32 v19, -v4, v6, 1.0
	v_fma_f32 v18, v19, v6, v6
	v_fma_f32 v5, -v4, v18, 1.0
	v_fma_f32 v5, v5, v6, v18
	v_mul_f32_e32 v2, v2, v5
	v_mul_f32_e32 v2, v3, v2
	v_cvt_pk_bf16_f32 v2, v2, s0
	global_store_short v[34:35], v2, off offset:1152
	v_add_f32_e32 v2, v24, v130
	v_min_f32_e32 v2, 0x40e00000, v2
	v_mul_f32_e32 v4, 0x3fd9db23, v2
	v_mul_f32_e32 v4, 0xbfb8aa3b, v4
	v_exp_f32_e32 v4, v4
	v_add_f32_e32 v3, v8, v131
	v_med3_f32 v3, v3, s36, v225
	v_add_f32_e32 v3, 1.0, v3
	v_add_f32_e32 v4, 1.0, v4
	v_rcp_f32_e32 v6, v4
	s_nop 0
	v_fma_f32 v7, -v4, v6, 1.0
	v_fmac_f32_e32 v6, v7, v6
	v_fma_f32 v18, -v4, v6, 1.0
	v_fma_f32 v8, v18, v6, v6
	v_fma_f32 v5, -v4, v8, 1.0
	v_fma_f32 v5, v5, v6, v8
	v_mul_f32_e32 v2, v2, v5
	v_mul_f32_e32 v2, v3, v2
	v_cvt_pk_bf16_f32 v2, v2, s0
	global_store_short v[34:35], v2, off offset:1280
	v_add_f32_e32 v2, v25, v130
	v_min_f32_e32 v2, 0x40e00000, v2
	v_mul_f32_e32 v4, 0x3fd9db23, v2
	v_mul_f32_e32 v4, 0xbfb8aa3b, v4
	v_exp_f32_e32 v4, v4
	v_add_f32_e32 v3, v9, v131
	v_med3_f32 v3, v3, s36, v225
	v_add_f32_e32 v3, 1.0, v3
	v_add_f32_e32 v4, 1.0, v4
	v_rcp_f32_e32 v6, v4
	s_nop 0
	v_fma_f32 v7, -v4, v6, 1.0
	v_fmac_f32_e32 v6, v7, v6
	v_fma_f32 v9, -v4, v6, 1.0
	v_fma_f32 v8, v9, v6, v6
	v_fma_f32 v5, -v4, v8, 1.0
	v_fma_f32 v5, v5, v6, v8
; DI u16 f2bf(float a) { return (u16)(pack2(a, 0.f) & 0xffffu); }
; DI float sigmoidf_(float x) { return 1.f / (1.f + __expf(-x)); }
; DI void moe1_phase(const P& p, int l, unsigned char* lds) {
;     ...
;     for (int mt = 0; mt < 4; ++mt)
; #pragma unroll
;       for (int i = 0; i < 16; ++i) {
;         float ug = fminf(acc[mt][0][i] + bg, 7.f);
;         float ul = fminf(fmaxf(acc[mt][1][i] + bl, -7.f), 7.f);
;         float a = ug * sigmoidf_(1.702f * ug) * (ul + 1.f);
;         abase[(mt * 32 + 8 * (i >> 2) + (i & 3)) * 64] = f2bf(a);
;       }
	v_mul_f32_e32 v2, v2, v5
	v_mul_f32_e32 v2, v3, v2
	v_cvt_pk_bf16_f32 v2, v2, s0
	global_store_short v[34:35], v2, off offset:1408
	v_add_f32_e32 v2, v26, v130
	v_min_f32_e32 v2, 0x40e00000, v2
	v_mul_f32_e32 v4, 0x3fd9db23, v2
	v_mul_f32_e32 v4, 0xbfb8aa3b, v4
	v_exp_f32_e32 v4, v4
	v_add_f32_e32 v3, v10, v131
	v_med3_f32 v3, v3, s36, v225
	v_add_f32_e32 v3, 1.0, v3
	v_add_f32_e32 v4, 1.0, v4
	v_rcp_f32_e32 v6, v4
	s_nop 0
	v_fma_f32 v7, -v4, v6, 1.0
	v_fmac_f32_e32 v6, v7, v6
	v_fma_f32 v9, -v4, v6, 1.0
	v_fma_f32 v8, v9, v6, v6
	v_fma_f32 v5, -v4, v8, 1.0
	v_fma_f32 v5, v5, v6, v8
	v_mul_f32_e32 v2, v2, v5
	v_mul_f32_e32 v2, v3, v2
	v_cvt_pk_bf16_f32 v2, v2, s0
	global_store_short v[34:35], v2, off offset:2048
	v_add_f32_e32 v2, v27, v130
	v_min_f32_e32 v2, 0x40e00000, v2
	v_mul_f32_e32 v4, 0x3fd9db23, v2
	v_mul_f32_e32 v4, 0xbfb8aa3b, v4
	v_exp_f32_e32 v4, v4
	v_add_f32_e32 v3, v11, v131
	v_med3_f32 v3, v3, s36, v225
	v_add_f32_e32 v3, 1.0, v3
	v_add_f32_e32 v4, 1.0, v4
	v_rcp_f32_e32 v6, v4
	s_nop 0
	v_fma_f32 v7, -v4, v6, 1.0
	v_fmac_f32_e32 v6, v7, v6
	v_fma_f32 v9, -v4, v6, 1.0
	v_fma_f32 v8, v9, v6, v6
	v_fma_f32 v5, -v4, v8, 1.0
	v_fma_f32 v5, v5, v6, v8
	v_mul_f32_e32 v2, v2, v5
	v_mul_f32_e32 v2, v3, v2
	v_cvt_pk_bf16_f32 v2, v2, s0
	global_store_short v[34:35], v2, off offset:2176
	v_add_f32_e32 v2, v28, v130
	v_min_f32_e32 v2, 0x40e00000, v2
	v_mul_f32_e32 v4, 0x3fd9db23, v2
	v_mul_f32_e32 v4, 0xbfb8aa3b, v4
	v_exp_f32_e32 v4, v4
	v_add_f32_e32 v3, v12, v131
	v_med3_f32 v3, v3, s36, v225
	v_add_f32_e32 v3, 1.0, v3
	v_add_f32_e32 v4, 1.0, v4
	v_rcp_f32_e32 v6, v4
	s_nop 0
	v_fma_f32 v7, -v4, v6, 1.0
	v_fmac_f32_e32 v6, v7, v6
	v_fma_f32 v9, -v4, v6, 1.0
	v_fma_f32 v8, v9, v6, v6
	v_fma_f32 v5, -v4, v8, 1.0
	v_fma_f32 v5, v5, v6, v8
	v_mul_f32_e32 v2, v2, v5
	v_mul_f32_e32 v2, v3, v2
	v_cvt_pk_bf16_f32 v2, v2, s0
	global_store_short v[34:35], v2, off offset:2304
	v_add_f32_e32 v2, v29, v130
	v_min_f32_e32 v2, 0x40e00000, v2
	v_mul_f32_e32 v4, 0x3fd9db23, v2
	v_mul_f32_e32 v4, 0xbfb8aa3b, v4
	v_exp_f32_e32 v4, v4
	v_add_f32_e32 v3, v13, v131
	v_med3_f32 v3, v3, s36, v225
	v_add_f32_e32 v3, 1.0, v3
	v_add_f32_e32 v4, 1.0, v4
	v_rcp_f32_e32 v6, v4
	s_nop 0
	v_fma_f32 v7, -v4, v6, 1.0
	v_fmac_f32_e32 v6, v7, v6
	v_fma_f32 v9, -v4, v6, 1.0
	v_fma_f32 v8, v9, v6, v6
	v_fma_f32 v5, -v4, v8, 1.0
	v_fma_f32 v5, v5, v6, v8
	v_mul_f32_e32 v2, v2, v5
	v_mul_f32_e32 v2, v3, v2
	v_cvt_pk_bf16_f32 v2, v2, s0
	global_store_short v[34:35], v2, off offset:2432
	v_add_f32_e32 v2, v30, v130
	v_min_f32_e32 v2, 0x40e00000, v2
	v_mul_f32_e32 v4, 0x3fd9db23, v2
	v_mul_f32_e32 v4, 0xbfb8aa3b, v4
	v_exp_f32_e32 v4, v4
	v_add_f32_e32 v3, v14, v131
	v_med3_f32 v3, v3, s36, v225
	v_add_f32_e32 v3, 1.0, v3
	v_add_f32_e32 v4, 1.0, v4
	v_rcp_f32_e32 v6, v4
	s_nop 0
	v_fma_f32 v7, -v4, v6, 1.0
	v_fmac_f32_e32 v6, v7, v6
	v_fma_f32 v9, -v4, v6, 1.0
	v_fma_f32 v8, v9, v6, v6
	v_fma_f32 v5, -v4, v8, 1.0
	v_fma_f32 v5, v5, v6, v8
	v_mul_f32_e32 v2, v2, v5
	v_mul_f32_e32 v2, v3, v2
	v_cvt_pk_bf16_f32 v2, v2, s0
	global_store_short v[34:35], v2, off offset:3072
	v_add_f32_e32 v2, v31, v130
	v_min_f32_e32 v2, 0x40e00000, v2
	v_mul_f32_e32 v4, 0x3fd9db23, v2
	v_mul_f32_e32 v4, 0xbfb8aa3b, v4
	v_exp_f32_e32 v4, v4
	v_add_f32_e32 v3, v15, v131
	v_med3_f32 v3, v3, s36, v225
	v_add_f32_e32 v3, 1.0, v3
	v_add_f32_e32 v4, 1.0, v4
	v_rcp_f32_e32 v6, v4
	s_nop 0
	v_fma_f32 v7, -v4, v6, 1.0
	v_fmac_f32_e32 v6, v7, v6
	v_fma_f32 v9, -v4, v6, 1.0
	v_fma_f32 v8, v9, v6, v6
	v_fma_f32 v5, -v4, v8, 1.0
	v_fma_f32 v5, v5, v6, v8
	v_mul_f32_e32 v2, v2, v5
	v_mul_f32_e32 v2, v3, v2
	v_cvt_pk_bf16_f32 v2, v2, s0
	global_store_short v[34:35], v2, off offset:3200
	v_add_f32_e32 v2, v32, v130
	v_min_f32_e32 v2, 0x40e00000, v2
	v_mul_f32_e32 v4, 0x3fd9db23, v2
	v_mul_f32_e32 v4, 0xbfb8aa3b, v4
	v_exp_f32_e32 v4, v4
	v_add_f32_e32 v3, v16, v131
	v_med3_f32 v3, v3, s36, v225
	v_add_f32_e32 v3, 1.0, v3
	v_add_f32_e32 v4, 1.0, v4
	v_rcp_f32_e32 v6, v4
	s_nop 0
	v_fma_f32 v7, -v4, v6, 1.0
	v_fmac_f32_e32 v6, v7, v6
	v_fma_f32 v9, -v4, v6, 1.0
	v_fma_f32 v8, v9, v6, v6
	v_fma_f32 v5, -v4, v8, 1.0
	v_fma_f32 v5, v5, v6, v8
	v_mul_f32_e32 v2, v2, v5
	v_mul_f32_e32 v2, v3, v2
	v_cvt_pk_bf16_f32 v2, v2, s0
	global_store_short v[34:35], v2, off offset:3328
	v_add_f32_e32 v2, v33, v130
	v_min_f32_e32 v2, 0x40e00000, v2
	v_mul_f32_e32 v4, 0x3fd9db23, v2
	v_mul_f32_e32 v4, 0xbfb8aa3b, v4
	v_exp_f32_e32 v4, v4
	v_add_f32_e32 v3, v17, v131
	v_med3_f32 v3, v3, s36, v225
	v_add_f32_e32 v3, 1.0, v3
	v_add_f32_e32 v4, 1.0, v4
	v_rcp_f32_e32 v6, v4
	s_nop 0
	v_fma_f32 v7, -v4, v6, 1.0
	v_fmac_f32_e32 v6, v7, v6
	v_fma_f32 v9, -v4, v6, 1.0
	v_fma_f32 v8, v9, v6, v6
	v_fma_f32 v5, -v4, v8, 1.0
	v_fma_f32 v5, v5, v6, v8
	v_mul_f32_e32 v2, v2, v5
	v_mul_f32_e32 v2, v3, v2
	v_cvt_pk_bf16_f32 v2, v2, s0
	global_store_short v[34:35], v2, off offset:3456
	s_branch .LBB0_1416
